# MFMA pair order within each 16-MFMA group changed so consecutive accumulate pairs share one fragment operand (snake order), GEMM1/2/4
# speedup vs baseline: 1.0063x; 1.0017x over previous
; #define PG8_STAGE(bufoff, gbase, voff) do { _Pragma("unroll") for (int _i = 0; _i < 2; ++_i) \
;         __builtin_amdgcn_global_load_lds((const unsigned*)((const char*)(gbase) + (voff)[_i]), (PG8_LAS unsigned*)(lds + (bufoff) + ldsw + _i * 8192), 16, 0, 0); } while (0)
; #define PG8_LDA(dst, b, h) do { _Pragma("unroll") for (int m = 0; m < 4; ++m) _Pragma("unroll") for (int k = 0; k < 2; ++k) dst[m][k] = *(const PG8_LAS bf16x8*)(lds + PG8_SA(b, h) + aoff + m * 2048 + k * 1024); } while (0)
; #define PG8_LDB(dst, b, h) do { _Pragma("unroll") for (int n = 0; n < 2; ++n) _Pragma("unroll") for (int k = 0; k < 2; ++k) dst[n][k] = *(const PG8_LAS bf16x8*)(lds + PG8_SB(b, h) + boff + n * 2048 + k * 1024); } while (0)
; #define PG8_MMA(ai, bj, At, Bt) do { __builtin_amdgcn_s_setprio(1); _Pragma("unroll") for (int m = 0; m < 4; ++m) _Pragma("unroll") for (int n = 0; n < 2; ++n) _Pragma("unroll") for (int k = 0; k < 2; ++k) \
;         acc[ai][bj][m][n] = __builtin_amdgcn_mfma_f32_16x16x32_bf16(Bt[n][k], At[m][k], acc[ai][bj][m][n], 0, 0, 0); __builtin_amdgcn_s_setprio(0); } while (0)
; #define PG8_WAIT_V(n) asm volatile("s_waitcnt vmcnt(" #n ")" ::: "memory")
; #define PG8_WAIT_L(n) asm volatile("s_waitcnt lgkmcnt(" #n ")" ::: "memory")
; #define PG8_BAR __builtin_amdgcn_s_barrier()
; #define PG8_SCHED __builtin_amdgcn_sched_barrier(0)
; template <class Epi, class Sched, bool ALIGN_EPI = false, bool SP2 = false>
; __device__ __forceinline__ void gemm_phase(PG8_LAS unsigned char* lds, const Gemm g, const Sched& S, const Epi& E) {
;     ...
;             PG8_LDB(B0, 0, 0); PG8_LDB(B1, 0, 1); PG8_SCHED; PG8_LDA(At, 0, 0); PG8_STAGE(PG8_SA(1, 1), a1 + hstep, voffA);
;             PG8_WAIT_V(8); PG8_WAIT_L(0); PG8_BAR; PG8_MMA(0, 0, At, B0); PG8_MMA(0, 1, At, B1); PG8_BAR; PG8_SCHED;
;             PG8_LDA(At, 0, 1); PG8_STAGE(PG8_SB(0, 0), b2, voffB); PG8_STAGE(PG8_SB(0, 1), b2 + hstep, voffB); PG8_STAGE(PG8_SA(0, 0), a2, voffA);
;             PG8_WAIT_V(8); PG8_WAIT_L(0); PG8_BAR; PG8_MMA(1, 0, At, B0); PG8_MMA(1, 1, At, B1); PG8_BAR; PG8_SCHED;
.LBB0_366:
	ds_read_b128 v[130:133], v228
	ds_read_b128 v[134:137], v228 offset:1024
	ds_read_b128 v[138:141], v228 offset:2048
	ds_read_b128 v[170:173], v228 offset:3072
	ds_read_b128 v[174:177], v229
	ds_read_b128 v[178:181], v229 offset:1024
	ds_read_b128 v[182:185], v229 offset:2048
	ds_read_b128 v[186:189], v229 offset:3072
	s_add_u32 s12, s10, 0xfff00080
	s_addc_u32 s13, s11, -1
	s_cmp_eq_u32 s80, 60
	s_cselect_b32 s15, s0, s13
	s_cselect_b32 s14, s1, s12
	s_cselect_b32 s13, s61, s77
	s_cselect_b32 s12, s69, s71
	s_add_i32 m0, s79, 0xc000
	ds_read_b128 v[190:193], v230
	ds_read_b128 v[194:197], v230 offset:1024
	ds_read_b128 v[198:201], v230 offset:2048
	ds_read_b128 v[202:205], v230 offset:3072
	ds_read_b128 v[206:209], v230 offset:4096
	ds_read_b128 v[210:213], v230 offset:5120
	ds_read_b128 v[214:217], v230 offset:6144
	ds_read_b128 v[218:221], v230 offset:7168
	global_load_lds_dwordx4 v164, s[10:11]
	s_add_i32 m0, s79, 0xe000
	s_nop 0
	global_load_lds_dwordx4 v166, s[10:11]
	s_waitcnt vmcnt(8)
	s_waitcnt lgkmcnt(0)
	s_barrier
	s_waitcnt lgkmcnt(0)
	v_mfma_f32_16x16x32_bf16 v[126:129], v[130:133], v[190:193], v[126:129]
	v_mfma_f32_16x16x32_bf16 v[126:129], v[134:137], v[194:197], v[126:129]
	v_mfma_f32_16x16x32_bf16 v[122:125], v[138:141], v[190:193], v[122:125]
	v_mfma_f32_16x16x32_bf16 v[122:125], v[170:173], v[194:197], v[122:125]
	v_mfma_f32_16x16x32_bf16 v[106:109], v[138:141], v[198:201], v[106:109]
	v_mfma_f32_16x16x32_bf16 v[106:109], v[170:173], v[202:205], v[106:109]
	v_mfma_f32_16x16x32_bf16 v[110:113], v[130:133], v[198:201], v[110:113]
	v_mfma_f32_16x16x32_bf16 v[110:113], v[134:137], v[202:205], v[110:113]
	v_mfma_f32_16x16x32_bf16 v[94:97], v[130:133], v[206:209], v[94:97]
	v_mfma_f32_16x16x32_bf16 v[94:97], v[134:137], v[210:213], v[94:97]
	v_mfma_f32_16x16x32_bf16 v[90:93], v[138:141], v[206:209], v[90:93]
	v_mfma_f32_16x16x32_bf16 v[90:93], v[170:173], v[210:213], v[90:93]
	v_mfma_f32_16x16x32_bf16 v[74:77], v[138:141], v[214:217], v[74:77]
	v_mfma_f32_16x16x32_bf16 v[74:77], v[170:173], v[218:221], v[74:77]
	v_mfma_f32_16x16x32_bf16 v[78:81], v[130:133], v[214:217], v[78:81]
	v_mfma_f32_16x16x32_bf16 v[78:81], v[134:137], v[218:221], v[78:81]
	v_mfma_f32_16x16x32_bf16 v[118:121], v[174:177], v[190:193], v[118:121]
	v_mfma_f32_16x16x32_bf16 v[118:121], v[178:181], v[194:197], v[118:121]
	v_mfma_f32_16x16x32_bf16 v[114:117], v[182:185], v[190:193], v[114:117]
	v_mfma_f32_16x16x32_bf16 v[114:117], v[186:189], v[194:197], v[114:117]
	v_mfma_f32_16x16x32_bf16 v[98:101], v[182:185], v[198:201], v[98:101]
	v_mfma_f32_16x16x32_bf16 v[98:101], v[186:189], v[202:205], v[98:101]
	v_mfma_f32_16x16x32_bf16 v[102:105], v[174:177], v[198:201], v[102:105]
	v_mfma_f32_16x16x32_bf16 v[102:105], v[178:181], v[202:205], v[102:105]
	v_mfma_f32_16x16x32_bf16 v[86:89], v[174:177], v[206:209], v[86:89]
	v_mfma_f32_16x16x32_bf16 v[86:89], v[178:181], v[210:213], v[86:89]
	v_mfma_f32_16x16x32_bf16 v[82:85], v[182:185], v[206:209], v[82:85]
	v_mfma_f32_16x16x32_bf16 v[82:85], v[186:189], v[210:213], v[82:85]
	v_mfma_f32_16x16x32_bf16 v[66:69], v[182:185], v[214:217], v[66:69]
	v_mfma_f32_16x16x32_bf16 v[66:69], v[186:189], v[218:221], v[66:69]
	v_mfma_f32_16x16x32_bf16 v[70:73], v[174:177], v[214:217], v[70:73]
	v_mfma_f32_16x16x32_bf16 v[70:73], v[178:181], v[218:221], v[70:73]
	s_barrier
	s_add_i32 s81, s63, s67
	s_mov_b32 m0, s81
	ds_read_b128 v[190:193], v230 offset:16384
	ds_read_b128 v[194:197], v230 offset:17408
	ds_read_b128 v[198:201], v230 offset:18432
	ds_read_b128 v[202:205], v230 offset:19456
	ds_read_b128 v[206:209], v230 offset:20480
	ds_read_b128 v[210:213], v230 offset:21504
	ds_read_b128 v[214:217], v230 offset:22528
	ds_read_b128 v[218:221], v230 offset:23552
	global_load_lds_dwordx4 v144, s[12:13]
	s_add_i32 m0, s81, 0x2000
	s_add_u32 s82, s12, 0x100000
	s_addc_u32 s83, s13, 0
	s_add_i32 s81, s94, s67
	global_load_lds_dwordx4 v148, s[12:13]
	s_mov_b32 m0, s81
	s_nop 0
	global_load_lds_dwordx4 v144, s[82:83]
	s_add_i32 m0, s81, 0x2000
	s_nop 0
	global_load_lds_dwordx4 v148, s[82:83]
	s_mov_b32 m0, s79
	s_nop 0
	global_load_lds_dwordx4 v142, s[14:15]
	s_mov_b32 m0, s88
	s_nop 0
	global_load_lds_dwordx4 v146, s[14:15]
	s_waitcnt vmcnt(8)
	s_waitcnt lgkmcnt(0)
	s_barrier
	s_waitcnt lgkmcnt(0)
	v_mfma_f32_16x16x32_bf16 v[62:65], v[130:133], v[190:193], v[62:65]
	v_mfma_f32_16x16x32_bf16 v[62:65], v[134:137], v[194:197], v[62:65]
	v_mfma_f32_16x16x32_bf16 v[58:61], v[138:141], v[190:193], v[58:61]
	v_mfma_f32_16x16x32_bf16 v[58:61], v[170:173], v[194:197], v[58:61]
	v_mfma_f32_16x16x32_bf16 v[42:45], v[138:141], v[198:201], v[42:45]
	v_mfma_f32_16x16x32_bf16 v[42:45], v[170:173], v[202:205], v[42:45]
	v_mfma_f32_16x16x32_bf16 v[46:49], v[130:133], v[198:201], v[46:49]
	v_mfma_f32_16x16x32_bf16 v[46:49], v[134:137], v[202:205], v[46:49]
	v_mfma_f32_16x16x32_bf16 v[30:33], v[130:133], v[206:209], v[30:33]
	v_mfma_f32_16x16x32_bf16 v[30:33], v[134:137], v[210:213], v[30:33]
	v_mfma_f32_16x16x32_bf16 v[26:29], v[138:141], v[206:209], v[26:29]
	v_mfma_f32_16x16x32_bf16 v[26:29], v[170:173], v[210:213], v[26:29]
	v_mfma_f32_16x16x32_bf16 v[10:13], v[138:141], v[214:217], v[10:13]
	v_mfma_f32_16x16x32_bf16 v[10:13], v[170:173], v[218:221], v[10:13]
	v_mfma_f32_16x16x32_bf16 v[14:17], v[130:133], v[214:217], v[14:17]
	v_mfma_f32_16x16x32_bf16 v[14:17], v[134:137], v[218:221], v[14:17]
	v_mfma_f32_16x16x32_bf16 v[54:57], v[174:177], v[190:193], v[54:57]
	v_mfma_f32_16x16x32_bf16 v[54:57], v[178:181], v[194:197], v[54:57]
	v_mfma_f32_16x16x32_bf16 v[50:53], v[182:185], v[190:193], v[50:53]
	v_mfma_f32_16x16x32_bf16 v[50:53], v[186:189], v[194:197], v[50:53]
	v_mfma_f32_16x16x32_bf16 v[34:37], v[182:185], v[198:201], v[34:37]
	v_mfma_f32_16x16x32_bf16 v[34:37], v[186:189], v[202:205], v[34:37]
	v_mfma_f32_16x16x32_bf16 v[38:41], v[174:177], v[198:201], v[38:41]
	v_mfma_f32_16x16x32_bf16 v[38:41], v[178:181], v[202:205], v[38:41]
	v_mfma_f32_16x16x32_bf16 v[22:25], v[174:177], v[206:209], v[22:25]
	v_mfma_f32_16x16x32_bf16 v[22:25], v[178:181], v[210:213], v[22:25]
	v_mfma_f32_16x16x32_bf16 v[18:21], v[182:185], v[206:209], v[18:21]
	v_mfma_f32_16x16x32_bf16 v[18:21], v[186:189], v[210:213], v[18:21]
	v_mfma_f32_16x16x32_bf16 v[2:5], v[182:185], v[214:217], v[2:5]
	v_mfma_f32_16x16x32_bf16 v[2:5], v[186:189], v[218:221], v[2:5]
	v_mfma_f32_16x16x32_bf16 v[6:9], v[174:177], v[214:217], v[6:9]
	v_mfma_f32_16x16x32_bf16 v[6:9], v[178:181], v[218:221], v[6:9]
	s_barrier
; #define PG8_STAGE(bufoff, gbase, voff) do { _Pragma("unroll") for (int _i = 0; _i < 2; ++_i) \
;         __builtin_amdgcn_global_load_lds((const unsigned*)((const char*)(gbase) + (voff)[_i]), (PG8_LAS unsigned*)(lds + (bufoff) + ldsw + _i * 8192), 16, 0, 0); } while (0)
; #define PG8_LDA(dst, b, h) do { _Pragma("unroll") for (int m = 0; m < 4; ++m) _Pragma("unroll") for (int k = 0; k < 2; ++k) dst[m][k] = *(const PG8_LAS bf16x8*)(lds + PG8_SA(b, h) + aoff + m * 2048 + k * 1024); } while (0)
; #define PG8_LDB(dst, b, h) do { _Pragma("unroll") for (int n = 0; n < 2; ++n) _Pragma("unroll") for (int k = 0; k < 2; ++k) dst[n][k] = *(const PG8_LAS bf16x8*)(lds + PG8_SB(b, h) + boff + n * 2048 + k * 1024); } while (0)
; #define PG8_MMA(ai, bj, At, Bt) do { __builtin_amdgcn_s_setprio(1); _Pragma("unroll") for (int m = 0; m < 4; ++m) _Pragma("unroll") for (int n = 0; n < 2; ++n) _Pragma("unroll") for (int k = 0; k < 2; ++k) \
;         acc[ai][bj][m][n] = __builtin_amdgcn_mfma_f32_16x16x32_bf16(Bt[n][k], At[m][k], acc[ai][bj][m][n], 0, 0, 0); __builtin_amdgcn_s_setprio(0); } while (0)
; #define PG8_WAIT_V(n) asm volatile("s_waitcnt vmcnt(" #n ")" ::: "memory")
; #define PG8_WAIT_L(n) asm volatile("s_waitcnt lgkmcnt(" #n ")" ::: "memory")
; #define PG8_BAR __builtin_amdgcn_s_barrier()
; #define PG8_SCHED __builtin_amdgcn_sched_barrier(0)
; template <class Epi, class Sched, bool ALIGN_EPI = false, bool SP2 = false>
; __device__ __forceinline__ void gemm_phase(PG8_LAS unsigned char* lds, const Gemm g, const Sched& S, const Epi& E) {
;     ...
;             PG8_LDB(B0, 1, 0); PG8_LDB(B1, 1, 1); PG8_SCHED; PG8_LDA(At, 1, 0); PG8_STAGE(PG8_SA(0, 1), a2 + hstep, voffA);
;             PG8_WAIT_V(8); PG8_WAIT_L(0); PG8_BAR; PG8_MMA(0, 0, At, B0); PG8_MMA(0, 1, At, B1); PG8_BAR; PG8_SCHED;
;             PG8_LDA(At, 1, 1); PG8_STAGE(PG8_SB(1, 0), b3, voffB); PG8_STAGE(PG8_SB(1, 1), b3 + hstep, voffB); PG8_STAGE(PG8_SA(1, 0), a3, voffA);
;             PG8_WAIT_V(8); PG8_WAIT_L(0); PG8_BAR; PG8_MMA(1, 0, At, B0); PG8_MMA(1, 1, At, B1); PG8_BAR; PG8_SCHED;
	s_add_i32 s81, 0, 0x18000
	v_add_u32_e32 v150, s81, v153
	s_add_i32 s82, 0, 0x1c000
	ds_read_b128 v[130:133], v150
	ds_read_b128 v[134:137], v150 offset:1024
	ds_read_b128 v[138:141], v150 offset:2048
	ds_read_b128 v[170:173], v150 offset:3072
	v_add_u32_e32 v150, s82, v153
	ds_read_b128 v[174:177], v150
	ds_read_b128 v[178:181], v150 offset:1024
	ds_read_b128 v[182:185], v150 offset:2048
	ds_read_b128 v[186:189], v150 offset:3072
	s_add_u32 s14, s14, 0x100000
	s_addc_u32 s15, s15, 0
	s_mov_b32 m0, s89
	ds_read_b128 v[190:193], v230 offset:32768
	ds_read_b128 v[194:197], v230 offset:33792
	ds_read_b128 v[198:201], v230 offset:34816
	ds_read_b128 v[202:205], v230 offset:35840
	ds_read_b128 v[206:209], v230 offset:36864
	ds_read_b128 v[210:213], v230 offset:37888
	ds_read_b128 v[214:217], v230 offset:38912
	ds_read_b128 v[218:221], v230 offset:39936
	global_load_lds_dwordx4 v142, s[14:15]
	s_mov_b32 m0, s90
	s_nop 0
	global_load_lds_dwordx4 v146, s[14:15]
	s_waitcnt vmcnt(8)
	s_waitcnt lgkmcnt(0)
	s_barrier
	s_waitcnt lgkmcnt(0)
	v_mfma_f32_16x16x32_bf16 v[126:129], v[130:133], v[190:193], v[126:129]
	v_mfma_f32_16x16x32_bf16 v[126:129], v[134:137], v[194:197], v[126:129]
	v_mfma_f32_16x16x32_bf16 v[122:125], v[138:141], v[190:193], v[122:125]
	v_mfma_f32_16x16x32_bf16 v[122:125], v[170:173], v[194:197], v[122:125]
	v_mfma_f32_16x16x32_bf16 v[106:109], v[138:141], v[198:201], v[106:109]
	v_mfma_f32_16x16x32_bf16 v[106:109], v[170:173], v[202:205], v[106:109]
	v_mfma_f32_16x16x32_bf16 v[110:113], v[130:133], v[198:201], v[110:113]
	v_mfma_f32_16x16x32_bf16 v[110:113], v[134:137], v[202:205], v[110:113]
	v_mfma_f32_16x16x32_bf16 v[94:97], v[130:133], v[206:209], v[94:97]
	v_mfma_f32_16x16x32_bf16 v[94:97], v[134:137], v[210:213], v[94:97]
	v_mfma_f32_16x16x32_bf16 v[90:93], v[138:141], v[206:209], v[90:93]
	v_mfma_f32_16x16x32_bf16 v[90:93], v[170:173], v[210:213], v[90:93]
	v_mfma_f32_16x16x32_bf16 v[74:77], v[138:141], v[214:217], v[74:77]
	v_mfma_f32_16x16x32_bf16 v[74:77], v[170:173], v[218:221], v[74:77]
	v_mfma_f32_16x16x32_bf16 v[78:81], v[130:133], v[214:217], v[78:81]
	v_mfma_f32_16x16x32_bf16 v[78:81], v[134:137], v[218:221], v[78:81]
	v_mfma_f32_16x16x32_bf16 v[118:121], v[174:177], v[190:193], v[118:121]
	v_mfma_f32_16x16x32_bf16 v[118:121], v[178:181], v[194:197], v[118:121]
	v_mfma_f32_16x16x32_bf16 v[114:117], v[182:185], v[190:193], v[114:117]
	v_mfma_f32_16x16x32_bf16 v[114:117], v[186:189], v[194:197], v[114:117]
	v_mfma_f32_16x16x32_bf16 v[98:101], v[182:185], v[198:201], v[98:101]
	v_mfma_f32_16x16x32_bf16 v[98:101], v[186:189], v[202:205], v[98:101]
	v_mfma_f32_16x16x32_bf16 v[102:105], v[174:177], v[198:201], v[102:105]
	v_mfma_f32_16x16x32_bf16 v[102:105], v[178:181], v[202:205], v[102:105]
	v_mfma_f32_16x16x32_bf16 v[86:89], v[174:177], v[206:209], v[86:89]
	v_mfma_f32_16x16x32_bf16 v[86:89], v[178:181], v[210:213], v[86:89]
	v_mfma_f32_16x16x32_bf16 v[82:85], v[182:185], v[206:209], v[82:85]
	v_mfma_f32_16x16x32_bf16 v[82:85], v[186:189], v[210:213], v[82:85]
	v_mfma_f32_16x16x32_bf16 v[66:69], v[182:185], v[214:217], v[66:69]
	v_mfma_f32_16x16x32_bf16 v[66:69], v[186:189], v[218:221], v[66:69]
	v_mfma_f32_16x16x32_bf16 v[70:73], v[174:177], v[214:217], v[70:73]
	v_mfma_f32_16x16x32_bf16 v[70:73], v[178:181], v[218:221], v[70:73]
	s_barrier
	s_add_u32 s100, s14, 0xfff00080
	s_addc_u32 s101, s15, -1
	s_add_u32 s98, s12, 0x80
	s_addc_u32 s99, s13, 0
	s_add_i32 s14, s81, s67
	s_mov_b32 m0, s14
	ds_read_b128 v[190:193], v230 offset:49152
	ds_read_b128 v[194:197], v230 offset:50176
	ds_read_b128 v[198:201], v230 offset:51200
	ds_read_b128 v[202:205], v230 offset:52224
	ds_read_b128 v[206:209], v230 offset:53248
	ds_read_b128 v[210:213], v230 offset:54272
	ds_read_b128 v[214:217], v230 offset:55296
	ds_read_b128 v[218:221], v230 offset:56320
	global_load_lds_dwordx4 v144, s[98:99]
	s_add_i32 m0, s14, 0x2000
	s_add_u32 s12, s12, 0x100080
	s_addc_u32 s13, s13, 0
	s_add_i32 s14, s82, s67
	global_load_lds_dwordx4 v148, s[98:99]
	s_mov_b32 m0, s14
	s_nop 0
	global_load_lds_dwordx4 v144, s[12:13]
	s_add_i32 m0, s14, 0x2000
	s_nop 0
	global_load_lds_dwordx4 v148, s[12:13]
	s_mov_b32 m0, s93
	s_nop 0
	global_load_lds_dwordx4 v142, s[100:101]
	s_mov_b32 m0, s62
	s_nop 0
	global_load_lds_dwordx4 v146, s[100:101]
	s_waitcnt vmcnt(8)
	s_waitcnt lgkmcnt(0)
	s_barrier
	s_waitcnt lgkmcnt(0)
	v_mfma_f32_16x16x32_bf16 v[62:65], v[130:133], v[190:193], v[62:65]
	v_mfma_f32_16x16x32_bf16 v[62:65], v[134:137], v[194:197], v[62:65]
	v_mfma_f32_16x16x32_bf16 v[58:61], v[138:141], v[190:193], v[58:61]
	v_mfma_f32_16x16x32_bf16 v[58:61], v[170:173], v[194:197], v[58:61]
	v_mfma_f32_16x16x32_bf16 v[42:45], v[138:141], v[198:201], v[42:45]
	v_mfma_f32_16x16x32_bf16 v[42:45], v[170:173], v[202:205], v[42:45]
	v_mfma_f32_16x16x32_bf16 v[46:49], v[130:133], v[198:201], v[46:49]
	v_mfma_f32_16x16x32_bf16 v[46:49], v[134:137], v[202:205], v[46:49]
	v_mfma_f32_16x16x32_bf16 v[30:33], v[130:133], v[206:209], v[30:33]
	v_mfma_f32_16x16x32_bf16 v[30:33], v[134:137], v[210:213], v[30:33]
	v_mfma_f32_16x16x32_bf16 v[26:29], v[138:141], v[206:209], v[26:29]
	v_mfma_f32_16x16x32_bf16 v[26:29], v[170:173], v[210:213], v[26:29]
	v_mfma_f32_16x16x32_bf16 v[10:13], v[138:141], v[214:217], v[10:13]
	v_mfma_f32_16x16x32_bf16 v[10:13], v[170:173], v[218:221], v[10:13]
	v_mfma_f32_16x16x32_bf16 v[14:17], v[130:133], v[214:217], v[14:17]
	v_mfma_f32_16x16x32_bf16 v[14:17], v[134:137], v[218:221], v[14:17]
	v_mfma_f32_16x16x32_bf16 v[54:57], v[174:177], v[190:193], v[54:57]
	v_mfma_f32_16x16x32_bf16 v[54:57], v[178:181], v[194:197], v[54:57]
	v_mfma_f32_16x16x32_bf16 v[50:53], v[182:185], v[190:193], v[50:53]
	v_mfma_f32_16x16x32_bf16 v[50:53], v[186:189], v[194:197], v[50:53]
	v_mfma_f32_16x16x32_bf16 v[34:37], v[182:185], v[198:201], v[34:37]
	v_mfma_f32_16x16x32_bf16 v[34:37], v[186:189], v[202:205], v[34:37]
	v_mfma_f32_16x16x32_bf16 v[38:41], v[174:177], v[198:201], v[38:41]
	v_mfma_f32_16x16x32_bf16 v[38:41], v[178:181], v[202:205], v[38:41]
	v_mfma_f32_16x16x32_bf16 v[22:25], v[174:177], v[206:209], v[22:25]
	v_mfma_f32_16x16x32_bf16 v[22:25], v[178:181], v[210:213], v[22:25]
	v_mfma_f32_16x16x32_bf16 v[18:21], v[182:185], v[206:209], v[18:21]
	v_mfma_f32_16x16x32_bf16 v[18:21], v[186:189], v[210:213], v[18:21]
	v_mfma_f32_16x16x32_bf16 v[2:5], v[182:185], v[214:217], v[2:5]
	v_mfma_f32_16x16x32_bf16 v[2:5], v[186:189], v[218:221], v[2:5]
	v_mfma_f32_16x16x32_bf16 v[6:9], v[174:177], v[214:217], v[6:9]
	v_mfma_f32_16x16x32_bf16 v[6:9], v[178:181], v[218:221], v[6:9]
	s_barrier
	s_add_i32 s80, s80, 2
	s_add_u32 s10, s10, 0x100
	s_addc_u32 s11, s11, 0
	s_add_u32 s71, s71, 0x100
	s_addc_u32 s77, s77, 0
	s_cmp_gt_u32 s80, 61
	s_cbranch_scc0 .LBB0_366
	s_and_b64 vcc, exec, s[28:29]
	s_cbranch_vccz .LBB0_369
	s_barrier

; #define PG8_STAGE(bufoff, gbase, voff) do { _Pragma("unroll") for (int _i = 0; _i < 2; ++_i) \
;         __builtin_amdgcn_global_load_lds((const unsigned*)((const char*)(gbase) + (voff)[_i]), (PG8_LAS unsigned*)(lds + (bufoff) + ldsw + _i * 8192), 16, 0, 0); } while (0)
; #define PG8_LDA(dst, b, h) do { _Pragma("unroll") for (int m = 0; m < 4; ++m) _Pragma("unroll") for (int k = 0; k < 2; ++k) dst[m][k] = *(const PG8_LAS bf16x8*)(lds + PG8_SA(b, h) + aoff + m * 2048 + k * 1024); } while (0)
; #define PG8_LDB(dst, b, h) do { _Pragma("unroll") for (int n = 0; n < 2; ++n) _Pragma("unroll") for (int k = 0; k < 2; ++k) dst[n][k] = *(const PG8_LAS bf16x8*)(lds + PG8_SB(b, h) + boff + n * 2048 + k * 1024); } while (0)
; #define PG8_WAIT_V(n) asm volatile("s_waitcnt vmcnt(" #n ")" ::: "memory")
; #define PG8_WAIT_L(n) asm volatile("s_waitcnt lgkmcnt(" #n ")" ::: "memory")
; template <class Epi, class Sched, bool ALIGN_EPI = false, bool SP2 = false>
; __device__ __forceinline__ void gemm_phase(PG8_LAS unsigned char* lds, const Gemm g, const Sched& S, const Epi& E) {
;     ...
;         const char* nA = has_next ? (const char*)g.A + (size_t)nxt.pm * tstep + (size_t)nxt.kt0 * kstep : cA; const char* nB = has_next ? (const char*)g.Bt + (size_t)nxt.pn * tstep + (size_t)nxt.kt0 * kstep : cB;
;         const int ntc = cur.ntu;
;         for (int t = 0; t < ntc; t += 2) {
;             if constexpr (Epi::MID) { if (ntc == nt && t == (nt >> 1)) E.mid(acc, cur, wr, wc, fr, fq); }
;             const bool last = (t == ntc - 2);
;             const char* a1 = cA + (size_t)(t + 1) * kstep;
;             const char* a2 = last ? nA : cA + (size_t)(t + 2) * kstep; const char* b2 = last ? nB : cB + (size_t)(t + 2) * kstep;
;             const char* a3 = a2 + kstep; const char* b3 = b2 + kstep;
;             if (last && has_next) S.a_ready(nxt);
;             if constexpr (SP2) {
;             PG8_LDB(B0, 0, 0); PG8_LDB(B1, 0, 1); PG8_SCHED; PG8_LDA(At, 0, 0); PG8_STAGE(PG8_SA(1, 1), a1 + hstep, voffA);
;             PG8_WAIT_V(8); PG8_WAIT_L(0); PG8_BAR; PG8_MMA(0, 0, At, B0); PG8_MMA(0, 1, At, B1); PG8_BAR; PG8_SCHED;
;             PG8_LDA(At, 0, 1); PG8_STAGE(PG8_SB(0, 0), b2, voffB); PG8_STAGE(PG8_SB(0, 1), b2 + hstep, voffB); PG8_STAGE(PG8_SA(0, 0), a2, voffA);
;             PG8_WAIT_V(8); PG8_WAIT_L(0); PG8_BAR; PG8_MMA(1, 0, At, B0); PG8_MMA(1, 1, At, B1); PG8_BAR; PG8_SCHED;
.LBB0_2487:
	v_add_u32_e32 v3, s67, v183
	s_add_i32 s81, s50, 2
	ds_read_b128 v[154:157], v3
	ds_read_b128 v[158:161], v3 offset:1024
	ds_read_b128 v[162:165], v3 offset:2048
	ds_read_b128 v[166:169], v3 offset:3072
	v_add_u32_e32 v3, s68, v183
	s_add_u32 s51, s42, s46
	ds_read_b128 v[170:173], v3
	ds_read_b128 v[174:177], v3 offset:1024
	ds_read_b128 v[178:181], v3 offset:2048
	ds_read_b128 v[184:187], v3 offset:3072
	s_addc_u32 s52, s43, s47
	s_add_u32 s51, s51, 0x100
	s_addc_u32 s52, s52, 0
	s_add_u32 s82, s79, s46
	s_addc_u32 s83, s80, s47
	s_cmp_eq_u32 s9, s50
	s_cselect_b32 s53, s27, s52
	s_cselect_b32 s52, s35, s51
	s_cselect_b32 s51, s31, s83
	s_cselect_b32 s50, s78, s82
	v_lshl_add_u64 v[4:5], v[150:151], 0, s[46:47]
	s_add_i32 m0, s11, 0xc000
	ds_read_b128 v[188:191], v211
	ds_read_b128 v[192:195], v211 offset:1024
	ds_read_b128 v[196:199], v211 offset:2048
	ds_read_b128 v[200:203], v211 offset:3072
	ds_read_b128 v[204:207], v211 offset:4096
	ds_read_b128 v[212:215], v211 offset:5120
	ds_read_b128 v[216:219], v211 offset:6144
	ds_read_b128 v[220:223], v211 offset:7168
	global_load_lds_dwordx4 v[4:5], off
	v_lshl_add_u64 v[4:5], v[152:153], 0, s[46:47]
	s_add_i32 m0, s11, 0xe000
	s_nop 0
	global_load_lds_dwordx4 v[4:5], off
	s_waitcnt vmcnt(8)
	s_waitcnt lgkmcnt(0)
	s_barrier
	s_waitcnt lgkmcnt(0)
	v_mfma_f32_16x16x32_bf16 v[130:133], v[154:157], v[188:191], v[130:133]
	v_mfma_f32_16x16x32_bf16 v[130:133], v[158:161], v[192:195], v[130:133]
	v_mfma_f32_16x16x32_bf16 v[126:129], v[162:165], v[188:191], v[126:129]
	v_mfma_f32_16x16x32_bf16 v[126:129], v[166:169], v[192:195], v[126:129]
	v_mfma_f32_16x16x32_bf16 v[110:113], v[162:165], v[196:199], v[110:113]
	v_mfma_f32_16x16x32_bf16 v[110:113], v[166:169], v[200:203], v[110:113]
	v_mfma_f32_16x16x32_bf16 v[114:117], v[154:157], v[196:199], v[114:117]
	v_mfma_f32_16x16x32_bf16 v[114:117], v[158:161], v[200:203], v[114:117]
	v_mfma_f32_16x16x32_bf16 v[98:101], v[154:157], v[204:207], v[98:101]
	v_mfma_f32_16x16x32_bf16 v[98:101], v[158:161], v[212:215], v[98:101]
	v_mfma_f32_16x16x32_bf16 v[94:97], v[162:165], v[204:207], v[94:97]
	v_mfma_f32_16x16x32_bf16 v[94:97], v[166:169], v[212:215], v[94:97]
	v_mfma_f32_16x16x32_bf16 v[78:81], v[162:165], v[216:219], v[78:81]
	v_mfma_f32_16x16x32_bf16 v[78:81], v[166:169], v[220:223], v[78:81]
	v_mfma_f32_16x16x32_bf16 v[82:85], v[154:157], v[216:219], v[82:85]
	v_mfma_f32_16x16x32_bf16 v[82:85], v[158:161], v[220:223], v[82:85]
	v_mfma_f32_16x16x32_bf16 v[122:125], v[170:173], v[188:191], v[122:125]
	v_mfma_f32_16x16x32_bf16 v[122:125], v[174:177], v[192:195], v[122:125]
	v_mfma_f32_16x16x32_bf16 v[118:121], v[178:181], v[188:191], v[118:121]
	v_mfma_f32_16x16x32_bf16 v[118:121], v[184:187], v[192:195], v[118:121]
	v_mfma_f32_16x16x32_bf16 v[102:105], v[178:181], v[196:199], v[102:105]
	v_mfma_f32_16x16x32_bf16 v[102:105], v[184:187], v[200:203], v[102:105]
	v_mfma_f32_16x16x32_bf16 v[106:109], v[170:173], v[196:199], v[106:109]
	v_mfma_f32_16x16x32_bf16 v[106:109], v[174:177], v[200:203], v[106:109]
	v_mfma_f32_16x16x32_bf16 v[90:93], v[170:173], v[204:207], v[90:93]
	v_mfma_f32_16x16x32_bf16 v[90:93], v[174:177], v[212:215], v[90:93]
	v_mfma_f32_16x16x32_bf16 v[86:89], v[178:181], v[204:207], v[86:89]
	v_mfma_f32_16x16x32_bf16 v[86:89], v[184:187], v[212:215], v[86:89]
	v_mfma_f32_16x16x32_bf16 v[70:73], v[178:181], v[216:219], v[70:73]
	v_mfma_f32_16x16x32_bf16 v[70:73], v[184:187], v[220:223], v[70:73]
	v_mfma_f32_16x16x32_bf16 v[74:77], v[170:173], v[216:219], v[74:77]
	v_mfma_f32_16x16x32_bf16 v[74:77], v[174:177], v[220:223], v[74:77]
	s_barrier
	s_add_i32 s82, s67, s55
	s_mov_b32 m0, s82
	ds_read_b128 v[188:191], v211 offset:16384
	ds_read_b128 v[192:195], v211 offset:17408
	ds_read_b128 v[196:199], v211 offset:18432
	ds_read_b128 v[200:203], v211 offset:19456
	ds_read_b128 v[204:207], v211 offset:20480
	ds_read_b128 v[212:215], v211 offset:21504
	ds_read_b128 v[216:219], v211 offset:22528
	ds_read_b128 v[220:223], v211 offset:23552
	global_load_lds_dwordx4 v134, s[50:51]
	s_add_i32 m0, s82, 0x2000
	s_add_u32 s82, s50, 0x100000
	s_addc_u32 s83, s51, 0
	s_add_i32 s84, s68, s55
	global_load_lds_dwordx4 v136, s[50:51]
	s_mov_b32 m0, s84
	s_nop 0
	global_load_lds_dwordx4 v134, s[82:83]
	s_add_i32 m0, s84, 0x2000
	s_nop 0
	global_load_lds_dwordx4 v136, s[82:83]
	s_mov_b32 m0, s11
	s_nop 0
	global_load_lds_dwordx4 v134, s[52:53]
	s_mov_b32 m0, s57
	s_nop 0
	global_load_lds_dwordx4 v136, s[52:53]
	s_waitcnt vmcnt(8)
	s_waitcnt lgkmcnt(0)
	s_barrier
; #define PG8_STAGE(bufoff, gbase, voff) do { _Pragma("unroll") for (int _i = 0; _i < 2; ++_i) \
;         __builtin_amdgcn_global_load_lds((const unsigned*)((const char*)(gbase) + (voff)[_i]), (PG8_LAS unsigned*)(lds + (bufoff) + ldsw + _i * 8192), 16, 0, 0); } while (0)
; #define PG8_LDA(dst, b, h) do { _Pragma("unroll") for (int m = 0; m < 4; ++m) _Pragma("unroll") for (int k = 0; k < 2; ++k) dst[m][k] = *(const PG8_LAS bf16x8*)(lds + PG8_SA(b, h) + aoff + m * 2048 + k * 1024); } while (0)
; #define PG8_LDB(dst, b, h) do { _Pragma("unroll") for (int n = 0; n < 2; ++n) _Pragma("unroll") for (int k = 0; k < 2; ++k) dst[n][k] = *(const PG8_LAS bf16x8*)(lds + PG8_SB(b, h) + boff + n * 2048 + k * 1024); } while (0)
; #define PG8_MMA(ai, bj, At, Bt) do { __builtin_amdgcn_s_setprio(1); _Pragma("unroll") for (int m = 0; m < 4; ++m) _Pragma("unroll") for (int n = 0; n < 2; ++n) _Pragma("unroll") for (int k = 0; k < 2; ++k) \
;         acc[ai][bj][m][n] = __builtin_amdgcn_mfma_f32_16x16x32_bf16(Bt[n][k], At[m][k], acc[ai][bj][m][n], 0, 0, 0); __builtin_amdgcn_s_setprio(0); } while (0)
; #define PG8_WAIT_V(n) asm volatile("s_waitcnt vmcnt(" #n ")" ::: "memory")
; #define PG8_WAIT_L(n) asm volatile("s_waitcnt lgkmcnt(" #n ")" ::: "memory")
; #define PG8_BAR __builtin_amdgcn_s_barrier()
; #define PG8_SCHED __builtin_amdgcn_sched_barrier(0)
; template <class Epi, class Sched, bool ALIGN_EPI = false, bool SP2 = false>
; __device__ __forceinline__ void gemm_phase(PG8_LAS unsigned char* lds, const Gemm g, const Sched& S, const Epi& E) {
;     ...
;             PG8_WAIT_V(8); PG8_WAIT_L(0); PG8_BAR; PG8_MMA(1, 0, At, B0); PG8_MMA(1, 1, At, B1); PG8_BAR; PG8_SCHED;
;             PG8_LDB(B0, 1, 0); PG8_LDB(B1, 1, 1); PG8_SCHED; PG8_LDA(At, 1, 0); PG8_STAGE(PG8_SA(0, 1), a2 + hstep, voffA);
;             PG8_WAIT_V(8); PG8_WAIT_L(0); PG8_BAR; PG8_MMA(0, 0, At, B0); PG8_MMA(0, 1, At, B1); PG8_BAR; PG8_SCHED;
	s_waitcnt lgkmcnt(0)
	v_mfma_f32_16x16x32_bf16 v[66:69], v[154:157], v[188:191], v[66:69]
	v_mfma_f32_16x16x32_bf16 v[66:69], v[158:161], v[192:195], v[66:69]
	v_mfma_f32_16x16x32_bf16 v[62:65], v[162:165], v[188:191], v[62:65]
	v_mfma_f32_16x16x32_bf16 v[62:65], v[166:169], v[192:195], v[62:65]
	v_mfma_f32_16x16x32_bf16 v[46:49], v[162:165], v[196:199], v[46:49]
	v_mfma_f32_16x16x32_bf16 v[46:49], v[166:169], v[200:203], v[46:49]
	v_mfma_f32_16x16x32_bf16 v[50:53], v[154:157], v[196:199], v[50:53]
	v_mfma_f32_16x16x32_bf16 v[50:53], v[158:161], v[200:203], v[50:53]
	v_mfma_f32_16x16x32_bf16 v[34:37], v[154:157], v[204:207], v[34:37]
	v_mfma_f32_16x16x32_bf16 v[34:37], v[158:161], v[212:215], v[34:37]
	v_mfma_f32_16x16x32_bf16 v[30:33], v[162:165], v[204:207], v[30:33]
	v_mfma_f32_16x16x32_bf16 v[30:33], v[166:169], v[212:215], v[30:33]
	v_mfma_f32_16x16x32_bf16 v[14:17], v[162:165], v[216:219], v[14:17]
	v_mfma_f32_16x16x32_bf16 v[14:17], v[166:169], v[220:223], v[14:17]
	v_mfma_f32_16x16x32_bf16 v[18:21], v[154:157], v[216:219], v[18:21]
	v_mfma_f32_16x16x32_bf16 v[18:21], v[158:161], v[220:223], v[18:21]
	v_mfma_f32_16x16x32_bf16 v[58:61], v[170:173], v[188:191], v[58:61]
	v_mfma_f32_16x16x32_bf16 v[58:61], v[174:177], v[192:195], v[58:61]
	v_mfma_f32_16x16x32_bf16 v[54:57], v[178:181], v[188:191], v[54:57]
	v_mfma_f32_16x16x32_bf16 v[54:57], v[184:187], v[192:195], v[54:57]
	v_mfma_f32_16x16x32_bf16 v[42:45], v[170:173], v[196:199], v[42:45]
	v_mfma_f32_16x16x32_bf16 v[42:45], v[174:177], v[200:203], v[42:45]
	v_mfma_f32_16x16x32_bf16 v[38:41], v[178:181], v[196:199], v[38:41]
	v_mfma_f32_16x16x32_bf16 v[38:41], v[184:187], v[200:203], v[38:41]
	v_mfma_f32_16x16x32_bf16 v[26:29], v[170:173], v[204:207], v[26:29]
	v_mfma_f32_16x16x32_bf16 v[26:29], v[174:177], v[212:215], v[26:29]
	v_mfma_f32_16x16x32_bf16 v[22:25], v[178:181], v[204:207], v[22:25]
	v_mfma_f32_16x16x32_bf16 v[22:25], v[184:187], v[212:215], v[22:25]
	v_mfma_f32_16x16x32_bf16 v[10:13], v[170:173], v[216:219], v[10:13]
	v_mfma_f32_16x16x32_bf16 v[10:13], v[174:177], v[220:223], v[10:13]
	v_mfma_f32_16x16x32_bf16 v[4:7], v[178:181], v[216:219], v[6:9]
	v_mfma_f32_16x16x32_bf16 v[4:7], v[184:187], v[220:223], v[4:7]
	s_barrier
	s_add_i32 s82, 0, 0x18000
	v_add_u32_e32 v3, s82, v183
	s_add_i32 s83, 0, 0x1c000
	ds_read_b128 v[154:157], v3
	ds_read_b128 v[158:161], v3 offset:1024
	ds_read_b128 v[162:165], v3 offset:2048
	ds_read_b128 v[166:169], v3 offset:3072
	v_add_u32_e32 v3, s83, v183
	ds_read_b128 v[170:173], v3
	ds_read_b128 v[174:177], v3 offset:1024
	ds_read_b128 v[178:181], v3 offset:2048
	ds_read_b128 v[184:187], v3 offset:3072
	s_add_u32 s52, s52, 0x100000
	s_addc_u32 s53, s53, 0
	s_mov_b32 m0, s60
	ds_read_b128 v[188:191], v211 offset:32768
	ds_read_b128 v[192:195], v211 offset:33792
	ds_read_b128 v[196:199], v211 offset:34816
	ds_read_b128 v[200:203], v211 offset:35840
	ds_read_b128 v[204:207], v211 offset:36864
	ds_read_b128 v[212:215], v211 offset:37888
	ds_read_b128 v[216:219], v211 offset:38912
	ds_read_b128 v[220:223], v211 offset:39936
	global_load_lds_dwordx4 v134, s[52:53]
	s_mov_b32 m0, s61
	s_nop 0
	global_load_lds_dwordx4 v136, s[52:53]
	s_waitcnt vmcnt(8)
	s_waitcnt lgkmcnt(0)
	s_barrier
	s_waitcnt lgkmcnt(0)
	v_mfma_f32_16x16x32_bf16 v[130:133], v[154:157], v[188:191], v[130:133]
	v_mfma_f32_16x16x32_bf16 v[130:133], v[158:161], v[192:195], v[130:133]
	v_mfma_f32_16x16x32_bf16 v[126:129], v[162:165], v[188:191], v[126:129]
	v_mfma_f32_16x16x32_bf16 v[126:129], v[166:169], v[192:195], v[126:129]
	v_mfma_f32_16x16x32_bf16 v[110:113], v[162:165], v[196:199], v[110:113]
	v_mfma_f32_16x16x32_bf16 v[110:113], v[166:169], v[200:203], v[110:113]
	v_mfma_f32_16x16x32_bf16 v[114:117], v[154:157], v[196:199], v[114:117]
	v_mfma_f32_16x16x32_bf16 v[114:117], v[158:161], v[200:203], v[114:117]
	v_mfma_f32_16x16x32_bf16 v[98:101], v[154:157], v[204:207], v[98:101]
	v_mfma_f32_16x16x32_bf16 v[98:101], v[158:161], v[212:215], v[98:101]
	v_mfma_f32_16x16x32_bf16 v[94:97], v[162:165], v[204:207], v[94:97]
	v_mfma_f32_16x16x32_bf16 v[94:97], v[166:169], v[212:215], v[94:97]
	v_mfma_f32_16x16x32_bf16 v[78:81], v[162:165], v[216:219], v[78:81]
	v_mfma_f32_16x16x32_bf16 v[78:81], v[166:169], v[220:223], v[78:81]
	v_mfma_f32_16x16x32_bf16 v[82:85], v[154:157], v[216:219], v[82:85]
	v_mfma_f32_16x16x32_bf16 v[82:85], v[158:161], v[220:223], v[82:85]
	v_mfma_f32_16x16x32_bf16 v[122:125], v[170:173], v[188:191], v[122:125]
	v_mfma_f32_16x16x32_bf16 v[122:125], v[174:177], v[192:195], v[122:125]
	v_mfma_f32_16x16x32_bf16 v[118:121], v[178:181], v[188:191], v[118:121]
	v_mfma_f32_16x16x32_bf16 v[118:121], v[184:187], v[192:195], v[118:121]
	v_mfma_f32_16x16x32_bf16 v[102:105], v[178:181], v[196:199], v[102:105]
	v_mfma_f32_16x16x32_bf16 v[102:105], v[184:187], v[200:203], v[102:105]
	v_mfma_f32_16x16x32_bf16 v[106:109], v[170:173], v[196:199], v[106:109]
	v_mfma_f32_16x16x32_bf16 v[106:109], v[174:177], v[200:203], v[106:109]
	v_mfma_f32_16x16x32_bf16 v[90:93], v[170:173], v[204:207], v[90:93]
	v_mfma_f32_16x16x32_bf16 v[90:93], v[174:177], v[212:215], v[90:93]
	v_mfma_f32_16x16x32_bf16 v[86:89], v[178:181], v[204:207], v[86:89]
	v_mfma_f32_16x16x32_bf16 v[86:89], v[184:187], v[212:215], v[86:89]
	v_mfma_f32_16x16x32_bf16 v[70:73], v[178:181], v[216:219], v[70:73]
	v_mfma_f32_16x16x32_bf16 v[70:73], v[184:187], v[220:223], v[70:73]
	v_mfma_f32_16x16x32_bf16 v[74:77], v[170:173], v[216:219], v[74:77]
	v_mfma_f32_16x16x32_bf16 v[74:77], v[174:177], v[220:223], v[74:77]
	s_barrier
; #define PG8_STAGE(bufoff, gbase, voff) do { _Pragma("unroll") for (int _i = 0; _i < 2; ++_i) \
;         __builtin_amdgcn_global_load_lds((const unsigned*)((const char*)(gbase) + (voff)[_i]), (PG8_LAS unsigned*)(lds + (bufoff) + ldsw + _i * 8192), 16, 0, 0); } while (0)
; #define PG8_LDA(dst, b, h) do { _Pragma("unroll") for (int m = 0; m < 4; ++m) _Pragma("unroll") for (int k = 0; k < 2; ++k) dst[m][k] = *(const PG8_LAS bf16x8*)(lds + PG8_SA(b, h) + aoff + m * 2048 + k * 1024); } while (0)
; #define PG8_MMA(ai, bj, At, Bt) do { __builtin_amdgcn_s_setprio(1); _Pragma("unroll") for (int m = 0; m < 4; ++m) _Pragma("unroll") for (int n = 0; n < 2; ++n) _Pragma("unroll") for (int k = 0; k < 2; ++k) \
;         acc[ai][bj][m][n] = __builtin_amdgcn_mfma_f32_16x16x32_bf16(Bt[n][k], At[m][k], acc[ai][bj][m][n], 0, 0, 0); __builtin_amdgcn_s_setprio(0); } while (0)
; #define PG8_WAIT_V(n) asm volatile("s_waitcnt vmcnt(" #n ")" ::: "memory")
; #define PG8_WAIT_L(n) asm volatile("s_waitcnt lgkmcnt(" #n ")" ::: "memory")
; #define PG8_BAR __builtin_amdgcn_s_barrier()
; #define PG8_SCHED __builtin_amdgcn_sched_barrier(0)
; template <class Epi, class Sched, bool ALIGN_EPI = false, bool SP2 = false>
; __device__ __forceinline__ void gemm_phase(PG8_LAS unsigned char* lds, const Gemm g, const Sched& S, const Epi& E) {
;     ...
;         for (int t = 0; t < ntc; t += 2) {
;     ...
;             PG8_LDA(At, 1, 1); PG8_STAGE(PG8_SB(1, 0), b3, voffB); PG8_STAGE(PG8_SB(1, 1), b3 + hstep, voffB); PG8_STAGE(PG8_SA(1, 0), a3, voffA);
;             PG8_WAIT_V(8); PG8_WAIT_L(0); PG8_BAR; PG8_MMA(1, 0, At, B0); PG8_MMA(1, 1, At, B1); PG8_BAR; PG8_SCHED;
	s_add_u32 s100, s52, 0xfff00080
	s_addc_u32 s101, s53, -1
	s_add_u32 s98, s50, 0x80
	s_addc_u32 s99, s51, 0
	s_add_i32 s52, s82, s55
	s_mov_b32 m0, s52
	ds_read_b128 v[188:191], v211 offset:49152
	ds_read_b128 v[192:195], v211 offset:50176
	ds_read_b128 v[196:199], v211 offset:51200
	ds_read_b128 v[200:203], v211 offset:52224
	ds_read_b128 v[204:207], v211 offset:53248
	ds_read_b128 v[212:215], v211 offset:54272
	ds_read_b128 v[216:219], v211 offset:55296
	ds_read_b128 v[220:223], v211 offset:56320
	global_load_lds_dwordx4 v134, s[98:99]
	s_add_i32 m0, s52, 0x2000
	s_add_u32 s50, s50, 0x100080
	s_addc_u32 s51, s51, 0
	s_add_i32 s52, s83, s55
	global_load_lds_dwordx4 v136, s[98:99]
	s_mov_b32 m0, s52
	s_nop 0
	global_load_lds_dwordx4 v134, s[50:51]
	s_add_i32 m0, s52, 0x2000
	s_nop 0
	global_load_lds_dwordx4 v136, s[50:51]
	s_mov_b32 m0, s63
	s_nop 0
	global_load_lds_dwordx4 v134, s[100:101]
	s_mov_b32 m0, s64
	s_nop 0
	global_load_lds_dwordx4 v136, s[100:101]
	s_waitcnt vmcnt(8)
	s_waitcnt lgkmcnt(0)
	s_barrier
	s_waitcnt lgkmcnt(0)
	v_mfma_f32_16x16x32_bf16 v[66:69], v[154:157], v[188:191], v[66:69]
	v_mfma_f32_16x16x32_bf16 v[66:69], v[158:161], v[192:195], v[66:69]
	v_mfma_f32_16x16x32_bf16 v[62:65], v[162:165], v[188:191], v[62:65]
	v_mfma_f32_16x16x32_bf16 v[62:65], v[166:169], v[192:195], v[62:65]
	v_mfma_f32_16x16x32_bf16 v[46:49], v[162:165], v[196:199], v[46:49]
	v_mfma_f32_16x16x32_bf16 v[46:49], v[166:169], v[200:203], v[46:49]
	v_mfma_f32_16x16x32_bf16 v[50:53], v[154:157], v[196:199], v[50:53]
	v_mfma_f32_16x16x32_bf16 v[50:53], v[158:161], v[200:203], v[50:53]
	v_mfma_f32_16x16x32_bf16 v[34:37], v[154:157], v[204:207], v[34:37]
	v_mfma_f32_16x16x32_bf16 v[34:37], v[158:161], v[212:215], v[34:37]
	v_mfma_f32_16x16x32_bf16 v[30:33], v[162:165], v[204:207], v[30:33]
	v_mfma_f32_16x16x32_bf16 v[30:33], v[166:169], v[212:215], v[30:33]
	v_mfma_f32_16x16x32_bf16 v[14:17], v[162:165], v[216:219], v[14:17]
	v_mfma_f32_16x16x32_bf16 v[14:17], v[166:169], v[220:223], v[14:17]
	v_mfma_f32_16x16x32_bf16 v[18:21], v[154:157], v[216:219], v[18:21]
	v_mfma_f32_16x16x32_bf16 v[18:21], v[158:161], v[220:223], v[18:21]
	v_mfma_f32_16x16x32_bf16 v[58:61], v[170:173], v[188:191], v[58:61]
	v_mfma_f32_16x16x32_bf16 v[58:61], v[174:177], v[192:195], v[58:61]
	v_mfma_f32_16x16x32_bf16 v[54:57], v[178:181], v[188:191], v[54:57]
	v_mfma_f32_16x16x32_bf16 v[54:57], v[184:187], v[192:195], v[54:57]
	v_mfma_f32_16x16x32_bf16 v[42:45], v[170:173], v[196:199], v[42:45]
	v_mfma_f32_16x16x32_bf16 v[42:45], v[174:177], v[200:203], v[42:45]
	v_mfma_f32_16x16x32_bf16 v[38:41], v[178:181], v[196:199], v[38:41]
	v_mfma_f32_16x16x32_bf16 v[38:41], v[184:187], v[200:203], v[38:41]
	v_mfma_f32_16x16x32_bf16 v[26:29], v[170:173], v[204:207], v[26:29]
	v_mfma_f32_16x16x32_bf16 v[26:29], v[174:177], v[212:215], v[26:29]
	v_mfma_f32_16x16x32_bf16 v[22:25], v[178:181], v[204:207], v[22:25]
	v_mfma_f32_16x16x32_bf16 v[22:25], v[184:187], v[212:215], v[22:25]
	v_mfma_f32_16x16x32_bf16 v[8:11], v[170:173], v[216:219], v[10:13]
	v_mfma_f32_16x16x32_bf16 v[10:13], v[174:177], v[220:223], v[8:11]
	v_mfma_f32_16x16x32_bf16 v[4:7], v[178:181], v[216:219], v[4:7]
	v_mfma_f32_16x16x32_bf16 v[6:9], v[184:187], v[220:223], v[4:7]
	s_barrier
	s_add_u32 s46, s46, 0x100
	s_addc_u32 s47, s47, 0
	s_cmp_ge_i32 s81, s77
	s_cbranch_scc1 .LBB0_2489
	s_mov_b32 s50, s81
	s_branch .LBB0_2485

; #define PG8_STAGE(bufoff, gbase, voff) do { _Pragma("unroll") for (int _i = 0; _i < 2; ++_i) \
;         __builtin_amdgcn_global_load_lds((const unsigned*)((const char*)(gbase) + (voff)[_i]), (PG8_LAS unsigned*)(lds + (bufoff) + ldsw + _i * 8192), 16, 0, 0); } while (0)
; #define PG8_LDA(dst, b, h) do { _Pragma("unroll") for (int m = 0; m < 4; ++m) _Pragma("unroll") for (int k = 0; k < 2; ++k) dst[m][k] = *(const PG8_LAS bf16x8*)(lds + PG8_SA(b, h) + aoff + m * 2048 + k * 1024); } while (0)
; #define PG8_LDB(dst, b, h) do { _Pragma("unroll") for (int n = 0; n < 2; ++n) _Pragma("unroll") for (int k = 0; k < 2; ++k) dst[n][k] = *(const PG8_LAS bf16x8*)(lds + PG8_SB(b, h) + boff + n * 2048 + k * 1024); } while (0)
; #define PG8_WAIT_V(n) asm volatile("s_waitcnt vmcnt(" #n ")" ::: "memory")
; #define PG8_WAIT_L(n) asm volatile("s_waitcnt lgkmcnt(" #n ")" ::: "memory")
; template <class Epi, class Sched, bool ALIGN_EPI = false, bool SP2 = false>
; __device__ __forceinline__ void gemm_phase(PG8_LAS unsigned char* lds, const Gemm g, const Sched& S, const Epi& E) {
;     ...
;         const char* nA = has_next ? (const char*)g.A + (size_t)nxt.pm * tstep + (size_t)nxt.kt0 * kstep : cA; const char* nB = has_next ? (const char*)g.Bt + (size_t)nxt.pn * tstep + (size_t)nxt.kt0 * kstep : cB;
;         const int ntc = cur.ntu;
;         for (int t = 0; t < ntc; t += 2) {
;             if constexpr (Epi::MID) { if (ntc == nt && t == (nt >> 1)) E.mid(acc, cur, wr, wc, fr, fq); }
;             const bool last = (t == ntc - 2);
;             const char* a1 = cA + (size_t)(t + 1) * kstep;
;             const char* a2 = last ? nA : cA + (size_t)(t + 2) * kstep; const char* b2 = last ? nB : cB + (size_t)(t + 2) * kstep;
;             const char* a3 = a2 + kstep; const char* b3 = b2 + kstep;
;             if (last && has_next) S.a_ready(nxt);
;             if constexpr (SP2) {
;             PG8_LDB(B0, 0, 0); PG8_LDB(B1, 0, 1); PG8_SCHED; PG8_LDA(At, 0, 0); PG8_STAGE(PG8_SA(1, 1), a1 + hstep, voffA);
;             PG8_WAIT_V(8); PG8_WAIT_L(0); PG8_BAR; PG8_MMA(0, 0, At, B0); PG8_MMA(0, 1, At, B1); PG8_BAR; PG8_SCHED;
;             PG8_LDA(At, 0, 1); PG8_STAGE(PG8_SB(0, 0), b2, voffB); PG8_STAGE(PG8_SB(0, 1), b2 + hstep, voffB); PG8_STAGE(PG8_SA(0, 0), a2, voffA);
;             PG8_WAIT_V(8); PG8_WAIT_L(0); PG8_BAR; PG8_MMA(1, 0, At, B0); PG8_MMA(1, 1, At, B1); PG8_BAR; PG8_SCHED;
.LBB0_2650:
	ds_read_b128 v[10:13], v195
	ds_read_b128 v[14:17], v195 offset:1024
	ds_read_b128 v[42:45], v195 offset:2048
	ds_read_b128 v[46:49], v195 offset:3072
	ds_read_b128 v[50:53], v238
	ds_read_b128 v[54:57], v238 offset:1024
	ds_read_b128 v[58:61], v238 offset:2048
	ds_read_b128 v[62:65], v238 offset:3072
	s_add_u32 s88, s86, 0xfff00080
	s_addc_u32 s89, s87, -1
	s_cmp_eq_u32 s93, 60
	s_cselect_b32 s91, s19, s89
	s_cselect_b32 s90, s69, s88
	s_cselect_b32 s89, s77, s92
	s_cselect_b32 s88, s79, s85
	s_add_i32 m0, s62, 0xc000
	ds_read_b128 v[66:69], v239
	ds_read_b128 v[70:73], v239 offset:1024
	ds_read_b128 v[170:173], v239 offset:2048
	ds_read_b128 v[174:177], v239 offset:3072
	ds_read_b128 v[178:181], v239 offset:4096
	ds_read_b128 v[208:211], v239 offset:5120
	ds_read_b128 v[212:215], v239 offset:6144
	ds_read_b128 v[216:219], v239 offset:7168
	global_load_lds_dwordx4 v200, s[86:87]
	s_add_i32 m0, s62, 0xe000
	s_nop 0
	global_load_lds_dwordx4 v202, s[86:87]
	s_waitcnt vmcnt(8)
	s_waitcnt lgkmcnt(0)
	s_barrier
	s_waitcnt lgkmcnt(0)
	v_mfma_f32_16x16x32_bf16 v[6:9], v[10:13], v[66:69], v[6:9]
	v_mfma_f32_16x16x32_bf16 v[6:9], v[14:17], v[70:73], v[6:9]
	v_mfma_f32_16x16x32_bf16 v[2:5], v[42:45], v[66:69], v[2:5]
	v_mfma_f32_16x16x32_bf16 v[2:5], v[46:49], v[70:73], v[2:5]
	v_mfma_f32_16x16x32_bf16 v[154:157], v[42:45], v[170:173], v[154:157]
	v_mfma_f32_16x16x32_bf16 v[154:157], v[46:49], v[174:177], v[154:157]
	v_mfma_f32_16x16x32_bf16 v[158:161], v[10:13], v[170:173], v[158:161]
	v_mfma_f32_16x16x32_bf16 v[158:161], v[14:17], v[174:177], v[158:161]
	v_mfma_f32_16x16x32_bf16 v[142:145], v[10:13], v[178:181], v[142:145]
	v_mfma_f32_16x16x32_bf16 v[142:145], v[14:17], v[208:211], v[142:145]
	v_mfma_f32_16x16x32_bf16 v[138:141], v[42:45], v[178:181], v[138:141]
	v_mfma_f32_16x16x32_bf16 v[138:141], v[46:49], v[208:211], v[138:141]
	v_mfma_f32_16x16x32_bf16 v[122:125], v[42:45], v[212:215], v[122:125]
	v_mfma_f32_16x16x32_bf16 v[122:125], v[46:49], v[216:219], v[122:125]
	v_mfma_f32_16x16x32_bf16 v[126:129], v[10:13], v[212:215], v[126:129]
	v_mfma_f32_16x16x32_bf16 v[126:129], v[14:17], v[216:219], v[126:129]
	v_mfma_f32_16x16x32_bf16 v[166:169], v[50:53], v[66:69], v[166:169]
	v_mfma_f32_16x16x32_bf16 v[166:169], v[54:57], v[70:73], v[166:169]
	v_mfma_f32_16x16x32_bf16 v[66:69], v[58:61], v[66:69], v[162:165]
	v_mfma_f32_16x16x32_bf16 v[66:69], v[62:65], v[70:73], v[66:69]
	v_mfma_f32_16x16x32_bf16 v[146:149], v[58:61], v[170:173], v[146:149]
	v_mfma_f32_16x16x32_bf16 v[146:149], v[62:65], v[174:177], v[146:149]
	v_mfma_f32_16x16x32_bf16 v[134:137], v[50:53], v[178:181], v[134:137]
	v_mfma_f32_16x16x32_bf16 v[134:137], v[54:57], v[208:211], v[134:137]
	v_mfma_f32_16x16x32_bf16 v[130:133], v[58:61], v[178:181], v[130:133]
	v_mfma_f32_16x16x32_bf16 v[130:133], v[62:65], v[208:211], v[130:133]
	v_mfma_f32_16x16x32_bf16 v[118:121], v[50:53], v[212:215], v[118:121]
	v_mfma_f32_16x16x32_bf16 v[118:121], v[54:57], v[216:219], v[118:121]
	v_mfma_f32_16x16x32_bf16 v[114:117], v[58:61], v[212:215], v[114:117]
	v_mfma_f32_16x16x32_bf16 v[114:117], v[62:65], v[216:219], v[114:117]
	v_mfma_f32_16x16x32_bf16 v[70:73], v[50:53], v[170:173], v[150:153]
	v_mfma_f32_16x16x32_bf16 v[70:73], v[54:57], v[174:177], v[70:73]
	s_barrier
	s_add_i32 vcc_lo, s96, s61
	s_mov_b32 m0, vcc_lo
	ds_read_b128 v[150:153], v239 offset:16384
	ds_read_b128 v[162:165], v239 offset:17408
	ds_read_b128 v[170:173], v239 offset:18432
	ds_read_b128 v[174:177], v239 offset:19456
	ds_read_b128 v[178:181], v239 offset:20480
	ds_read_b128 v[208:211], v239 offset:21504
	ds_read_b128 v[212:215], v239 offset:22528
	ds_read_b128 v[216:219], v239 offset:23552
	global_load_lds_dwordx4 v186, s[88:89]
	s_add_i32 m0, vcc_lo, 0x2000
	s_add_u32 vcc_lo, s88, 0x100000
	s_addc_u32 vcc_hi, s89, 0
	s_add_i32 s58, s70, s61
	global_load_lds_dwordx4 v190, s[88:89]
	s_mov_b32 m0, s58
	s_nop 0
	global_load_lds_dwordx4 v186, vcc
	s_add_i32 m0, s58, 0x2000
	s_nop 0
	global_load_lds_dwordx4 v190, vcc
	s_mov_b32 m0, s62
	s_nop 0
	global_load_lds_dwordx4 v184, s[90:91]
	s_mov_b32 m0, s63
	s_nop 0
	global_load_lds_dwordx4 v188, s[90:91]
	s_waitcnt vmcnt(8)
	s_waitcnt lgkmcnt(0)
	s_barrier
	s_waitcnt lgkmcnt(0)
	v_mfma_f32_16x16x32_bf16 v[110:113], v[10:13], v[150:153], v[110:113]
	v_mfma_f32_16x16x32_bf16 v[110:113], v[14:17], v[162:165], v[110:113]
	v_mfma_f32_16x16x32_bf16 v[106:109], v[42:45], v[150:153], v[106:109]
	v_mfma_f32_16x16x32_bf16 v[106:109], v[46:49], v[162:165], v[106:109]
	v_mfma_f32_16x16x32_bf16 v[94:97], v[10:13], v[170:173], v[94:97]
	v_mfma_f32_16x16x32_bf16 v[94:97], v[14:17], v[174:177], v[94:97]
	v_mfma_f32_16x16x32_bf16 v[90:93], v[42:45], v[170:173], v[90:93]
	v_mfma_f32_16x16x32_bf16 v[90:93], v[46:49], v[174:177], v[90:93]
	v_mfma_f32_16x16x32_bf16 v[78:81], v[10:13], v[178:181], v[78:81]
	v_mfma_f32_16x16x32_bf16 v[78:81], v[14:17], v[208:211], v[78:81]
	v_mfma_f32_16x16x32_bf16 v[74:77], v[42:45], v[178:181], v[74:77]
	v_mfma_f32_16x16x32_bf16 v[74:77], v[46:49], v[208:211], v[74:77]
	v_mfma_f32_16x16x32_bf16 v[10:13], v[10:13], v[212:215], v[30:33]
	v_mfma_f32_16x16x32_bf16 v[10:13], v[14:17], v[216:219], v[10:13]
	v_mfma_f32_16x16x32_bf16 v[14:17], v[42:45], v[212:215], v[26:29]
	v_mfma_f32_16x16x32_bf16 v[14:17], v[46:49], v[216:219], v[14:17]
	v_mfma_f32_16x16x32_bf16 v[26:29], v[50:53], v[150:153], v[102:105]
	v_mfma_f32_16x16x32_bf16 v[42:45], v[54:57], v[162:165], v[26:29]
	v_mfma_f32_16x16x32_bf16 v[26:29], v[58:61], v[150:153], v[98:101]
	v_mfma_f32_16x16x32_bf16 v[46:49], v[62:65], v[162:165], v[26:29]
	v_mfma_f32_16x16x32_bf16 v[26:29], v[50:53], v[170:173], v[86:89]
	v_mfma_f32_16x16x32_bf16 v[86:89], v[54:57], v[174:177], v[26:29]
	v_mfma_f32_16x16x32_bf16 v[26:29], v[58:61], v[170:173], v[82:85]
	v_mfma_f32_16x16x32_bf16 v[82:85], v[62:65], v[174:177], v[26:29]
	v_mfma_f32_16x16x32_bf16 v[26:29], v[50:53], v[178:181], v[38:41]
	v_mfma_f32_16x16x32_bf16 v[38:41], v[54:57], v[208:211], v[26:29]
	v_mfma_f32_16x16x32_bf16 v[26:29], v[58:61], v[178:181], v[34:37]
	v_mfma_f32_16x16x32_bf16 v[34:37], v[62:65], v[208:211], v[26:29]
	v_mfma_f32_16x16x32_bf16 v[22:25], v[50:53], v[212:215], v[22:25]
	v_mfma_f32_16x16x32_bf16 v[22:25], v[54:57], v[216:219], v[22:25]
	v_mfma_f32_16x16x32_bf16 v[18:21], v[58:61], v[212:215], v[18:21]
	v_mfma_f32_16x16x32_bf16 v[18:21], v[62:65], v[216:219], v[18:21]
	s_barrier
; #define PG8_STAGE(bufoff, gbase, voff) do { _Pragma("unroll") for (int _i = 0; _i < 2; ++_i) \
;         __builtin_amdgcn_global_load_lds((const unsigned*)((const char*)(gbase) + (voff)[_i]), (PG8_LAS unsigned*)(lds + (bufoff) + ldsw + _i * 8192), 16, 0, 0); } while (0)
; #define PG8_LDA(dst, b, h) do { _Pragma("unroll") for (int m = 0; m < 4; ++m) _Pragma("unroll") for (int k = 0; k < 2; ++k) dst[m][k] = *(const PG8_LAS bf16x8*)(lds + PG8_SA(b, h) + aoff + m * 2048 + k * 1024); } while (0)
; #define PG8_LDB(dst, b, h) do { _Pragma("unroll") for (int n = 0; n < 2; ++n) _Pragma("unroll") for (int k = 0; k < 2; ++k) dst[n][k] = *(const PG8_LAS bf16x8*)(lds + PG8_SB(b, h) + boff + n * 2048 + k * 1024); } while (0)
; #define PG8_MMA(ai, bj, At, Bt) do { __builtin_amdgcn_s_setprio(1); _Pragma("unroll") for (int m = 0; m < 4; ++m) _Pragma("unroll") for (int n = 0; n < 2; ++n) _Pragma("unroll") for (int k = 0; k < 2; ++k) \
;         acc[ai][bj][m][n] = __builtin_amdgcn_mfma_f32_16x16x32_bf16(Bt[n][k], At[m][k], acc[ai][bj][m][n], 0, 0, 0); __builtin_amdgcn_s_setprio(0); } while (0)
; #define PG8_WAIT_V(n) asm volatile("s_waitcnt vmcnt(" #n ")" ::: "memory")
; #define PG8_WAIT_L(n) asm volatile("s_waitcnt lgkmcnt(" #n ")" ::: "memory")
; #define PG8_BAR __builtin_amdgcn_s_barrier()
; #define PG8_SCHED __builtin_amdgcn_sched_barrier(0)
; template <class Epi, class Sched, bool ALIGN_EPI = false, bool SP2 = false>
; __device__ __forceinline__ void gemm_phase(PG8_LAS unsigned char* lds, const Gemm g, const Sched& S, const Epi& E) {
;     ...
;             PG8_LDB(B0, 1, 0); PG8_LDB(B1, 1, 1); PG8_SCHED; PG8_LDA(At, 1, 0); PG8_STAGE(PG8_SA(0, 1), a2 + hstep, voffA);
;             PG8_WAIT_V(8); PG8_WAIT_L(0); PG8_BAR; PG8_MMA(0, 0, At, B0); PG8_MMA(0, 1, At, B1); PG8_BAR; PG8_SCHED;
;             PG8_LDA(At, 1, 1); PG8_STAGE(PG8_SB(1, 0), b3, voffB); PG8_STAGE(PG8_SB(1, 1), b3 + hstep, voffB); PG8_STAGE(PG8_SA(1, 0), a3, voffA);
;             PG8_WAIT_V(8); PG8_WAIT_L(0); PG8_BAR; PG8_MMA(1, 0, At, B0); PG8_MMA(1, 1, At, B1); PG8_BAR; PG8_SCHED;
	s_add_i32 s58, 0, 0x18000
	s_add_i32 s59, 0, 0x1c000
	v_add_u32_e32 v54, s58, v1
	v_add_u32_e32 v98, s59, v1
	ds_read_b128 v[26:29], v54
	ds_read_b128 v[30:33], v54 offset:1024
	ds_read_b128 v[50:53], v54 offset:2048
	ds_read_b128 v[54:57], v54 offset:3072
	ds_read_b128 v[58:61], v98
	ds_read_b128 v[62:65], v98 offset:1024
	ds_read_b128 v[170:173], v98 offset:2048
	ds_read_b128 v[174:177], v98 offset:3072
	s_add_u32 s90, s90, 0x100000
	s_addc_u32 s91, s91, 0
	s_mov_b32 m0, s73
	ds_read_b128 v[98:101], v239 offset:32768
	ds_read_b128 v[102:105], v239 offset:33792
	ds_read_b128 v[178:181], v239 offset:34816
	ds_read_b128 v[208:211], v239 offset:35840
	ds_read_b128 v[212:215], v239 offset:36864
	ds_read_b128 v[216:219], v239 offset:37888
	ds_read_b128 v[220:223], v239 offset:38912
	ds_read_b128 v[224:227], v239 offset:39936
	global_load_lds_dwordx4 v184, s[90:91]
	s_mov_b32 m0, s75
	s_nop 0
	global_load_lds_dwordx4 v188, s[90:91]
	s_waitcnt vmcnt(8)
	s_waitcnt lgkmcnt(0)
	s_barrier
	s_waitcnt lgkmcnt(0)
	v_mfma_f32_16x16x32_bf16 v[150:153], v[26:29], v[178:181], v[158:161]
	v_mfma_f32_16x16x32_bf16 v[158:161], v[30:33], v[208:211], v[150:153]
	v_mfma_f32_16x16x32_bf16 v[6:9], v[26:29], v[98:101], v[6:9]
	v_mfma_f32_16x16x32_bf16 v[6:9], v[30:33], v[102:105], v[6:9]
	v_mfma_f32_16x16x32_bf16 v[2:5], v[50:53], v[98:101], v[2:5]
	v_mfma_f32_16x16x32_bf16 v[2:5], v[54:57], v[102:105], v[2:5]
	v_mfma_f32_16x16x32_bf16 v[150:153], v[50:53], v[178:181], v[154:157]
	v_mfma_f32_16x16x32_bf16 v[154:157], v[54:57], v[208:211], v[150:153]
	v_mfma_f32_16x16x32_bf16 v[142:145], v[26:29], v[212:215], v[142:145]
	v_mfma_f32_16x16x32_bf16 v[142:145], v[30:33], v[216:219], v[142:145]
	v_mfma_f32_16x16x32_bf16 v[138:141], v[50:53], v[212:215], v[138:141]
	v_mfma_f32_16x16x32_bf16 v[138:141], v[54:57], v[216:219], v[138:141]
	v_mfma_f32_16x16x32_bf16 v[126:129], v[26:29], v[220:223], v[126:129]
	v_mfma_f32_16x16x32_bf16 v[126:129], v[30:33], v[224:227], v[126:129]
	v_mfma_f32_16x16x32_bf16 v[122:125], v[50:53], v[220:223], v[122:125]
	v_mfma_f32_16x16x32_bf16 v[122:125], v[54:57], v[224:227], v[122:125]
	v_mfma_f32_16x16x32_bf16 v[66:69], v[170:173], v[98:101], v[66:69]
	v_mfma_f32_16x16x32_bf16 v[162:165], v[174:177], v[102:105], v[66:69]
	v_mfma_f32_16x16x32_bf16 v[150:153], v[58:61], v[98:101], v[166:169]
	v_mfma_f32_16x16x32_bf16 v[166:169], v[62:65], v[102:105], v[150:153]
	v_mfma_f32_16x16x32_bf16 v[66:69], v[58:61], v[178:181], v[70:73]
	v_mfma_f32_16x16x32_bf16 v[150:153], v[62:65], v[208:211], v[66:69]
	v_mfma_f32_16x16x32_bf16 v[66:69], v[170:173], v[178:181], v[146:149]
	v_mfma_f32_16x16x32_bf16 v[146:149], v[174:177], v[208:211], v[66:69]
	v_mfma_f32_16x16x32_bf16 v[66:69], v[58:61], v[212:215], v[134:137]
	v_mfma_f32_16x16x32_bf16 v[134:137], v[62:65], v[216:219], v[66:69]
	v_mfma_f32_16x16x32_bf16 v[66:69], v[170:173], v[212:215], v[130:133]
	v_mfma_f32_16x16x32_bf16 v[130:133], v[174:177], v[216:219], v[66:69]
	v_mfma_f32_16x16x32_bf16 v[66:69], v[58:61], v[220:223], v[118:121]
	v_mfma_f32_16x16x32_bf16 v[118:121], v[62:65], v[224:227], v[66:69]
	v_mfma_f32_16x16x32_bf16 v[66:69], v[170:173], v[220:223], v[114:117]
	v_mfma_f32_16x16x32_bf16 v[114:117], v[174:177], v[224:227], v[66:69]
	s_barrier
	s_add_i32 s58, s58, s61
	s_add_u32 s100, s88, 0x80
	s_addc_u32 s101, s89, 0
	s_mov_b32 m0, s58
	s_nop 1
	ds_read_b128 v[66:69], v239 offset:49152
	ds_read_b128 v[70:73], v239 offset:50176
	ds_read_b128 v[178:181], v239 offset:51200
	ds_read_b128 v[208:211], v239 offset:52224
	ds_read_b128 v[212:215], v239 offset:53248
	ds_read_b128 v[216:219], v239 offset:54272
	ds_read_b128 v[220:223], v239 offset:55296
	ds_read_b128 v[224:227], v239 offset:56320
	global_load_lds_dwordx4 v186, s[100:101]
	s_add_i32 m0, s58, 0x2000
	s_add_i32 s58, s59, s61
	global_load_lds_dwordx4 v190, s[100:101]
	s_add_u32 s88, s88, 0x100080
	s_addc_u32 s89, s89, 0
	s_add_u32 s100, s90, 0xfff00080
	s_addc_u32 s101, s91, -1
	s_mov_b32 m0, s58
	s_nop 0
	global_load_lds_dwordx4 v186, s[88:89]
	s_add_i32 m0, s58, 0x2000
	s_nop 0
	global_load_lds_dwordx4 v190, s[88:89]
	s_mov_b32 m0, s29
	s_nop 0
	global_load_lds_dwordx4 v184, s[100:101]
	s_mov_b32 m0, s95
	s_nop 0
	global_load_lds_dwordx4 v188, s[100:101]
	s_waitcnt vmcnt(8)
	s_waitcnt lgkmcnt(0)
	s_barrier
	s_waitcnt lgkmcnt(0)
	v_mfma_f32_16x16x32_bf16 v[98:101], v[26:29], v[66:69], v[110:113]
	v_mfma_f32_16x16x32_bf16 v[110:113], v[30:33], v[70:73], v[98:101]
	v_mfma_f32_16x16x32_bf16 v[94:97], v[26:29], v[178:181], v[94:97]
	v_mfma_f32_16x16x32_bf16 v[94:97], v[30:33], v[208:211], v[94:97]
	v_mfma_f32_16x16x32_bf16 v[78:81], v[26:29], v[212:215], v[78:81]
	v_mfma_f32_16x16x32_bf16 v[78:81], v[30:33], v[216:219], v[78:81]
	v_mfma_f32_16x16x32_bf16 v[10:13], v[26:29], v[220:223], v[10:13]
	v_mfma_f32_16x16x32_bf16 v[30:33], v[30:33], v[224:227], v[10:13]
	v_mfma_f32_16x16x32_bf16 v[98:101], v[50:53], v[66:69], v[106:109]
	v_mfma_f32_16x16x32_bf16 v[106:109], v[54:57], v[70:73], v[98:101]
	v_mfma_f32_16x16x32_bf16 v[90:93], v[50:53], v[178:181], v[90:93]
	v_mfma_f32_16x16x32_bf16 v[90:93], v[54:57], v[208:211], v[90:93]
	v_mfma_f32_16x16x32_bf16 v[74:77], v[50:53], v[212:215], v[74:77]
	v_mfma_f32_16x16x32_bf16 v[74:77], v[54:57], v[216:219], v[74:77]
	v_mfma_f32_16x16x32_bf16 v[10:13], v[50:53], v[220:223], v[14:17]
	v_mfma_f32_16x16x32_bf16 v[26:29], v[54:57], v[224:227], v[10:13]
	v_mfma_f32_16x16x32_bf16 v[10:13], v[58:61], v[66:69], v[42:45]
	v_mfma_f32_16x16x32_bf16 v[102:105], v[62:65], v[70:73], v[10:13]
	v_mfma_f32_16x16x32_bf16 v[10:13], v[170:173], v[66:69], v[46:49]
	v_mfma_f32_16x16x32_bf16 v[98:101], v[174:177], v[70:73], v[10:13]
	v_mfma_f32_16x16x32_bf16 v[10:13], v[58:61], v[178:181], v[86:89]
	v_mfma_f32_16x16x32_bf16 v[86:89], v[62:65], v[208:211], v[10:13]
	v_mfma_f32_16x16x32_bf16 v[10:13], v[170:173], v[178:181], v[82:85]
	v_mfma_f32_16x16x32_bf16 v[82:85], v[174:177], v[208:211], v[10:13]
	v_mfma_f32_16x16x32_bf16 v[10:13], v[58:61], v[212:215], v[38:41]
	v_mfma_f32_16x16x32_bf16 v[38:41], v[62:65], v[216:219], v[10:13]
	v_mfma_f32_16x16x32_bf16 v[10:13], v[170:173], v[212:215], v[34:37]
	v_mfma_f32_16x16x32_bf16 v[34:37], v[174:177], v[216:219], v[10:13]
	v_mfma_f32_16x16x32_bf16 v[10:13], v[58:61], v[220:223], v[22:25]
	v_mfma_f32_16x16x32_bf16 v[22:25], v[62:65], v[224:227], v[10:13]
	v_mfma_f32_16x16x32_bf16 v[10:13], v[170:173], v[220:223], v[18:21]
	v_mfma_f32_16x16x32_bf16 v[18:21], v[174:177], v[224:227], v[10:13]
	s_barrier
	s_add_i32 s93, s93, 2
	s_add_u32 s86, s86, 0x100
	s_addc_u32 s87, s87, 0
	s_add_u32 s85, s85, 0x100
	s_addc_u32 s92, s92, 0
	s_cmp_gt_u32 s93, 61
	s_cbranch_scc0 .LBB0_2650
	s_and_b64 vcc, exec, s[42:43]
	s_cbranch_vccz .LBB0_2653
	s_barrier

; #define PG8_STAGE(bufoff, gbase, voff) do { _Pragma("unroll") for (int _i = 0; _i < 2; ++_i) \
;         __builtin_amdgcn_global_load_lds((const unsigned*)((const char*)(gbase) + (voff)[_i]), (PG8_LAS unsigned*)(lds + (bufoff) + ldsw + _i * 8192), 16, 0, 0); } while (0)
; #define PG8_LDA(dst, b, h) do { _Pragma("unroll") for (int m = 0; m < 4; ++m) _Pragma("unroll") for (int k = 0; k < 2; ++k) dst[m][k] = *(const PG8_LAS bf16x8*)(lds + PG8_SA(b, h) + aoff + m * 2048 + k * 1024); } while (0)
; #define PG8_LDB(dst, b, h) do { _Pragma("unroll") for (int n = 0; n < 2; ++n) _Pragma("unroll") for (int k = 0; k < 2; ++k) dst[n][k] = *(const PG8_LAS bf16x8*)(lds + PG8_SB(b, h) + boff + n * 2048 + k * 1024); } while (0)
; #define PG8_WAIT_V(n) asm volatile("s_waitcnt vmcnt(" #n ")" ::: "memory")
; #define PG8_WAIT_L(n) asm volatile("s_waitcnt lgkmcnt(" #n ")" ::: "memory")
; template <class Epi, class Sched, bool ALIGN_EPI = false, bool SP2 = false>
; __device__ __forceinline__ void gemm_phase(PG8_LAS unsigned char* lds, const Gemm g, const Sched& S, const Epi& E) {
;     ...
;         const char* nA = has_next ? (const char*)g.A + (size_t)nxt.pm * tstep + (size_t)nxt.kt0 * kstep : cA; const char* nB = has_next ? (const char*)g.Bt + (size_t)nxt.pn * tstep + (size_t)nxt.kt0 * kstep : cB;
;         const int ntc = cur.ntu;
;         for (int t = 0; t < ntc; t += 2) {
;             if constexpr (Epi::MID) { if (ntc == nt && t == (nt >> 1)) E.mid(acc, cur, wr, wc, fr, fq); }
;             const bool last = (t == ntc - 2);
;             const char* a1 = cA + (size_t)(t + 1) * kstep;
;             const char* a2 = last ? nA : cA + (size_t)(t + 2) * kstep; const char* b2 = last ? nB : cB + (size_t)(t + 2) * kstep;
;             const char* a3 = a2 + kstep; const char* b3 = b2 + kstep;
;             if (last && has_next) S.a_ready(nxt);
;             if constexpr (SP2) {
;             PG8_LDB(B0, 0, 0); PG8_LDB(B1, 0, 1); PG8_SCHED; PG8_LDA(At, 0, 0); PG8_STAGE(PG8_SA(1, 1), a1 + hstep, voffA);
;             PG8_WAIT_V(8); PG8_WAIT_L(0); PG8_BAR; PG8_MMA(0, 0, At, B0); PG8_MMA(0, 1, At, B1); PG8_BAR; PG8_SCHED;
;             PG8_LDA(At, 0, 1); PG8_STAGE(PG8_SB(0, 0), b2, voffB); PG8_STAGE(PG8_SB(0, 1), b2 + hstep, voffB); PG8_STAGE(PG8_SA(0, 0), a2, voffA);
;             PG8_WAIT_V(8); PG8_WAIT_L(0); PG8_BAR; PG8_MMA(1, 0, At, B0); PG8_MMA(1, 1, At, B1); PG8_BAR; PG8_SCHED;
.LBB0_3522:
	ds_read_b128 v[144:147], v177
	ds_read_b128 v[148:151], v177 offset:1024
	ds_read_b128 v[152:155], v177 offset:2048
	ds_read_b128 v[156:159], v177 offset:3072
	ds_read_b128 v[160:163], v178
	ds_read_b128 v[164:167], v178 offset:1024
	ds_read_b128 v[168:171], v178 offset:2048
	ds_read_b128 v[172:175], v178 offset:3072
	s_add_u32 s40, s38, 0x100
	s_addc_u32 s41, s39, 0
	s_cmp_eq_u32 s69, s71
	s_cselect_b32 s45, s35, s41
	s_cselect_b32 s44, s34, s40
	s_cselect_b32 s43, s37, s70
	s_cselect_b32 s42, s36, s31
	s_add_i32 m0, s51, 0xc000
	ds_read_b128 v[180:183], v179
	ds_read_b128 v[184:187], v179 offset:1024
	ds_read_b128 v[188:191], v179 offset:2048
	ds_read_b128 v[192:195], v179 offset:3072
	ds_read_b128 v[196:199], v179 offset:4096
	ds_read_b128 v[200:203], v179 offset:5120
	ds_read_b128 v[204:207], v179 offset:6144
	ds_read_b128 v[208:211], v179 offset:7168
	global_load_lds_dwordx4 v138, s[38:39]
	s_add_i32 m0, s51, 0xe000
	s_nop 0
	global_load_lds_dwordx4 v140, s[38:39]
	s_waitcnt vmcnt(8)
	s_waitcnt lgkmcnt(0)
	s_barrier
	s_waitcnt lgkmcnt(0)
	v_mfma_f32_16x16x32_bf16 v[126:129], v[144:147], v[180:183], v[126:129]
	v_mfma_f32_16x16x32_bf16 v[126:129], v[148:151], v[184:187], v[126:129]
	v_mfma_f32_16x16x32_bf16 v[122:125], v[152:155], v[180:183], v[122:125]
	v_mfma_f32_16x16x32_bf16 v[122:125], v[156:159], v[184:187], v[122:125]
	v_mfma_f32_16x16x32_bf16 v[106:109], v[152:155], v[188:191], v[106:109]
	v_mfma_f32_16x16x32_bf16 v[106:109], v[156:159], v[192:195], v[106:109]
	v_mfma_f32_16x16x32_bf16 v[110:113], v[144:147], v[188:191], v[110:113]
	v_mfma_f32_16x16x32_bf16 v[110:113], v[148:151], v[192:195], v[110:113]
	v_mfma_f32_16x16x32_bf16 v[94:97], v[144:147], v[196:199], v[94:97]
	v_mfma_f32_16x16x32_bf16 v[94:97], v[148:151], v[200:203], v[94:97]
	v_mfma_f32_16x16x32_bf16 v[90:93], v[152:155], v[196:199], v[90:93]
	v_mfma_f32_16x16x32_bf16 v[90:93], v[156:159], v[200:203], v[90:93]
	v_mfma_f32_16x16x32_bf16 v[74:77], v[152:155], v[204:207], v[74:77]
	v_mfma_f32_16x16x32_bf16 v[74:77], v[156:159], v[208:211], v[74:77]
	v_mfma_f32_16x16x32_bf16 v[78:81], v[144:147], v[204:207], v[78:81]
	v_mfma_f32_16x16x32_bf16 v[78:81], v[148:151], v[208:211], v[78:81]
	v_mfma_f32_16x16x32_bf16 v[118:121], v[160:163], v[180:183], v[118:121]
	v_mfma_f32_16x16x32_bf16 v[118:121], v[164:167], v[184:187], v[118:121]
	v_mfma_f32_16x16x32_bf16 v[114:117], v[168:171], v[180:183], v[114:117]
	v_mfma_f32_16x16x32_bf16 v[114:117], v[172:175], v[184:187], v[114:117]
	v_mfma_f32_16x16x32_bf16 v[98:101], v[168:171], v[188:191], v[98:101]
	v_mfma_f32_16x16x32_bf16 v[98:101], v[172:175], v[192:195], v[98:101]
	v_mfma_f32_16x16x32_bf16 v[102:105], v[160:163], v[188:191], v[102:105]
	v_mfma_f32_16x16x32_bf16 v[102:105], v[164:167], v[192:195], v[102:105]
	v_mfma_f32_16x16x32_bf16 v[86:89], v[160:163], v[196:199], v[86:89]
	v_mfma_f32_16x16x32_bf16 v[86:89], v[164:167], v[200:203], v[86:89]
	v_mfma_f32_16x16x32_bf16 v[82:85], v[168:171], v[196:199], v[82:85]
	v_mfma_f32_16x16x32_bf16 v[82:85], v[172:175], v[200:203], v[82:85]
	v_mfma_f32_16x16x32_bf16 v[66:69], v[168:171], v[204:207], v[66:69]
	v_mfma_f32_16x16x32_bf16 v[66:69], v[172:175], v[208:211], v[66:69]
	v_mfma_f32_16x16x32_bf16 v[70:73], v[160:163], v[204:207], v[70:73]
	v_mfma_f32_16x16x32_bf16 v[70:73], v[164:167], v[208:211], v[70:73]
	s_barrier
	s_add_i32 s38, s63, s50
	s_mov_b32 m0, s38
	ds_read_b128 v[180:183], v179 offset:16384
	ds_read_b128 v[184:187], v179 offset:17408
	ds_read_b128 v[188:191], v179 offset:18432
	ds_read_b128 v[192:195], v179 offset:19456
	ds_read_b128 v[196:199], v179 offset:20480
	ds_read_b128 v[200:203], v179 offset:21504
	ds_read_b128 v[204:207], v179 offset:22528
	ds_read_b128 v[208:211], v179 offset:23552
	global_load_lds_dwordx4 v130, s[42:43]
	s_add_i32 m0, s38, 0x2000
	s_add_u32 s38, s42, 0x300000
	s_addc_u32 s39, s43, 0
	s_add_i32 s58, s64, s50
	global_load_lds_dwordx4 v132, s[42:43]
	s_mov_b32 m0, s58
	s_nop 0
	global_load_lds_dwordx4 v130, s[38:39]
	s_add_i32 m0, s58, 0x2000
	s_nop 0
	global_load_lds_dwordx4 v132, s[38:39]
	s_mov_b32 m0, s51
	s_nop 0
	global_load_lds_dwordx4 v130, s[44:45]
	s_mov_b32 m0, s52
	s_nop 0
	global_load_lds_dwordx4 v132, s[44:45]
	s_waitcnt vmcnt(8)
	s_waitcnt lgkmcnt(0)
	s_barrier
	s_waitcnt lgkmcnt(0)
	v_mfma_f32_16x16x32_bf16 v[62:65], v[144:147], v[180:183], v[62:65]
	v_mfma_f32_16x16x32_bf16 v[62:65], v[148:151], v[184:187], v[62:65]
	v_mfma_f32_16x16x32_bf16 v[58:61], v[152:155], v[180:183], v[58:61]
	v_mfma_f32_16x16x32_bf16 v[58:61], v[156:159], v[184:187], v[58:61]
	v_mfma_f32_16x16x32_bf16 v[42:45], v[152:155], v[188:191], v[42:45]
	v_mfma_f32_16x16x32_bf16 v[42:45], v[156:159], v[192:195], v[42:45]
	v_mfma_f32_16x16x32_bf16 v[46:49], v[144:147], v[188:191], v[46:49]
	v_mfma_f32_16x16x32_bf16 v[46:49], v[148:151], v[192:195], v[46:49]
	v_mfma_f32_16x16x32_bf16 v[30:33], v[144:147], v[196:199], v[30:33]
	v_mfma_f32_16x16x32_bf16 v[30:33], v[148:151], v[200:203], v[30:33]
	v_mfma_f32_16x16x32_bf16 v[26:29], v[152:155], v[196:199], v[26:29]
	v_mfma_f32_16x16x32_bf16 v[26:29], v[156:159], v[200:203], v[26:29]
	v_mfma_f32_16x16x32_bf16 v[10:13], v[152:155], v[204:207], v[10:13]
	v_mfma_f32_16x16x32_bf16 v[10:13], v[156:159], v[208:211], v[10:13]
	v_mfma_f32_16x16x32_bf16 v[14:17], v[144:147], v[204:207], v[14:17]
	v_mfma_f32_16x16x32_bf16 v[14:17], v[148:151], v[208:211], v[14:17]
	v_mfma_f32_16x16x32_bf16 v[54:57], v[160:163], v[180:183], v[54:57]
	v_mfma_f32_16x16x32_bf16 v[54:57], v[164:167], v[184:187], v[54:57]
	v_mfma_f32_16x16x32_bf16 v[50:53], v[168:171], v[180:183], v[50:53]
	v_mfma_f32_16x16x32_bf16 v[50:53], v[172:175], v[184:187], v[50:53]
	v_mfma_f32_16x16x32_bf16 v[34:37], v[168:171], v[188:191], v[34:37]
	v_mfma_f32_16x16x32_bf16 v[34:37], v[172:175], v[192:195], v[34:37]
	v_mfma_f32_16x16x32_bf16 v[38:41], v[160:163], v[188:191], v[38:41]
	v_mfma_f32_16x16x32_bf16 v[38:41], v[164:167], v[192:195], v[38:41]
	v_mfma_f32_16x16x32_bf16 v[22:25], v[160:163], v[196:199], v[22:25]
	v_mfma_f32_16x16x32_bf16 v[22:25], v[164:167], v[200:203], v[22:25]
	v_mfma_f32_16x16x32_bf16 v[18:21], v[168:171], v[196:199], v[18:21]
	v_mfma_f32_16x16x32_bf16 v[18:21], v[172:175], v[200:203], v[18:21]
	v_mfma_f32_16x16x32_bf16 v[2:5], v[168:171], v[204:207], v[2:5]
	v_mfma_f32_16x16x32_bf16 v[2:5], v[172:175], v[208:211], v[2:5]
	v_mfma_f32_16x16x32_bf16 v[6:9], v[160:163], v[204:207], v[6:9]
	v_mfma_f32_16x16x32_bf16 v[6:9], v[164:167], v[208:211], v[6:9]
	s_barrier
; #define PG8_STAGE(bufoff, gbase, voff) do { _Pragma("unroll") for (int _i = 0; _i < 2; ++_i) \
;         __builtin_amdgcn_global_load_lds((const unsigned*)((const char*)(gbase) + (voff)[_i]), (PG8_LAS unsigned*)(lds + (bufoff) + ldsw + _i * 8192), 16, 0, 0); } while (0)
; #define PG8_LDA(dst, b, h) do { _Pragma("unroll") for (int m = 0; m < 4; ++m) _Pragma("unroll") for (int k = 0; k < 2; ++k) dst[m][k] = *(const PG8_LAS bf16x8*)(lds + PG8_SA(b, h) + aoff + m * 2048 + k * 1024); } while (0)
; #define PG8_LDB(dst, b, h) do { _Pragma("unroll") for (int n = 0; n < 2; ++n) _Pragma("unroll") for (int k = 0; k < 2; ++k) dst[n][k] = *(const PG8_LAS bf16x8*)(lds + PG8_SB(b, h) + boff + n * 2048 + k * 1024); } while (0)
; #define PG8_MMA(ai, bj, At, Bt) do { __builtin_amdgcn_s_setprio(1); _Pragma("unroll") for (int m = 0; m < 4; ++m) _Pragma("unroll") for (int n = 0; n < 2; ++n) _Pragma("unroll") for (int k = 0; k < 2; ++k) \
;         acc[ai][bj][m][n] = __builtin_amdgcn_mfma_f32_16x16x32_bf16(Bt[n][k], At[m][k], acc[ai][bj][m][n], 0, 0, 0); __builtin_amdgcn_s_setprio(0); } while (0)
; #define PG8_WAIT_V(n) asm volatile("s_waitcnt vmcnt(" #n ")" ::: "memory")
; #define PG8_WAIT_L(n) asm volatile("s_waitcnt lgkmcnt(" #n ")" ::: "memory")
; #define PG8_BAR __builtin_amdgcn_s_barrier()
; #define PG8_SCHED __builtin_amdgcn_sched_barrier(0)
; template <class Epi, class Sched, bool ALIGN_EPI = false, bool SP2 = false>
; __device__ __forceinline__ void gemm_phase(PG8_LAS unsigned char* lds, const Gemm g, const Sched& S, const Epi& E) {
;     ...
;             PG8_LDB(B0, 1, 0); PG8_LDB(B1, 1, 1); PG8_SCHED; PG8_LDA(At, 1, 0); PG8_STAGE(PG8_SA(0, 1), a2 + hstep, voffA);
;             PG8_WAIT_V(8); PG8_WAIT_L(0); PG8_BAR; PG8_MMA(0, 0, At, B0); PG8_MMA(0, 1, At, B1); PG8_BAR; PG8_SCHED;
;             PG8_LDA(At, 1, 1); PG8_STAGE(PG8_SB(1, 0), b3, voffB); PG8_STAGE(PG8_SB(1, 1), b3 + hstep, voffB); PG8_STAGE(PG8_SA(1, 0), a3, voffA);
;             PG8_WAIT_V(8); PG8_WAIT_L(0); PG8_BAR; PG8_MMA(1, 0, At, B0); PG8_MMA(1, 1, At, B1); PG8_BAR; PG8_SCHED;
	s_add_i32 s58, 0, 0x18000
	v_add_u32_e32 v134, s58, v1
	s_add_i32 s59, 0, 0x1c000
	ds_read_b128 v[144:147], v134
	ds_read_b128 v[148:151], v134 offset:1024
	ds_read_b128 v[152:155], v134 offset:2048
	ds_read_b128 v[156:159], v134 offset:3072
	v_add_u32_e32 v134, s59, v1
	ds_read_b128 v[160:163], v134
	ds_read_b128 v[164:167], v134 offset:1024
	ds_read_b128 v[168:171], v134 offset:2048
	ds_read_b128 v[172:175], v134 offset:3072
	s_add_u32 s38, s44, 0x300000
	s_addc_u32 s39, s45, 0
	s_mov_b32 m0, s53
	ds_read_b128 v[180:183], v179 offset:32768
	ds_read_b128 v[184:187], v179 offset:33792
	ds_read_b128 v[188:191], v179 offset:34816
	ds_read_b128 v[192:195], v179 offset:35840
	ds_read_b128 v[196:199], v179 offset:36864
	ds_read_b128 v[200:203], v179 offset:37888
	ds_read_b128 v[204:207], v179 offset:38912
	ds_read_b128 v[208:211], v179 offset:39936
	global_load_lds_dwordx4 v130, s[38:39]
	s_mov_b32 m0, s54
	s_nop 0
	global_load_lds_dwordx4 v132, s[38:39]
	s_waitcnt vmcnt(8)
	s_waitcnt lgkmcnt(0)
	s_barrier
	s_waitcnt lgkmcnt(0)
	v_mfma_f32_16x16x32_bf16 v[126:129], v[144:147], v[180:183], v[126:129]
	v_mfma_f32_16x16x32_bf16 v[126:129], v[148:151], v[184:187], v[126:129]
	v_mfma_f32_16x16x32_bf16 v[122:125], v[152:155], v[180:183], v[122:125]
	v_mfma_f32_16x16x32_bf16 v[122:125], v[156:159], v[184:187], v[122:125]
	v_mfma_f32_16x16x32_bf16 v[106:109], v[152:155], v[188:191], v[106:109]
	v_mfma_f32_16x16x32_bf16 v[106:109], v[156:159], v[192:195], v[106:109]
	v_mfma_f32_16x16x32_bf16 v[110:113], v[144:147], v[188:191], v[110:113]
	v_mfma_f32_16x16x32_bf16 v[110:113], v[148:151], v[192:195], v[110:113]
	v_mfma_f32_16x16x32_bf16 v[94:97], v[144:147], v[196:199], v[94:97]
	v_mfma_f32_16x16x32_bf16 v[94:97], v[148:151], v[200:203], v[94:97]
	v_mfma_f32_16x16x32_bf16 v[90:93], v[152:155], v[196:199], v[90:93]
	v_mfma_f32_16x16x32_bf16 v[90:93], v[156:159], v[200:203], v[90:93]
	v_mfma_f32_16x16x32_bf16 v[74:77], v[152:155], v[204:207], v[74:77]
	v_mfma_f32_16x16x32_bf16 v[74:77], v[156:159], v[208:211], v[74:77]
	v_mfma_f32_16x16x32_bf16 v[78:81], v[144:147], v[204:207], v[78:81]
	v_mfma_f32_16x16x32_bf16 v[78:81], v[148:151], v[208:211], v[78:81]
	v_mfma_f32_16x16x32_bf16 v[118:121], v[160:163], v[180:183], v[118:121]
	v_mfma_f32_16x16x32_bf16 v[118:121], v[164:167], v[184:187], v[118:121]
	v_mfma_f32_16x16x32_bf16 v[114:117], v[168:171], v[180:183], v[114:117]
	v_mfma_f32_16x16x32_bf16 v[114:117], v[172:175], v[184:187], v[114:117]
	v_mfma_f32_16x16x32_bf16 v[98:101], v[168:171], v[188:191], v[98:101]
	v_mfma_f32_16x16x32_bf16 v[98:101], v[172:175], v[192:195], v[98:101]
	v_mfma_f32_16x16x32_bf16 v[102:105], v[160:163], v[188:191], v[102:105]
	v_mfma_f32_16x16x32_bf16 v[102:105], v[164:167], v[192:195], v[102:105]
	v_mfma_f32_16x16x32_bf16 v[86:89], v[160:163], v[196:199], v[86:89]
	v_mfma_f32_16x16x32_bf16 v[86:89], v[164:167], v[200:203], v[86:89]
	v_mfma_f32_16x16x32_bf16 v[82:85], v[168:171], v[196:199], v[82:85]
	v_mfma_f32_16x16x32_bf16 v[82:85], v[172:175], v[200:203], v[82:85]
	v_mfma_f32_16x16x32_bf16 v[66:69], v[168:171], v[204:207], v[66:69]
	v_mfma_f32_16x16x32_bf16 v[66:69], v[172:175], v[208:211], v[66:69]
	v_mfma_f32_16x16x32_bf16 v[70:73], v[160:163], v[204:207], v[70:73]
	v_mfma_f32_16x16x32_bf16 v[70:73], v[164:167], v[208:211], v[70:73]
	s_barrier
	s_add_i32 s38, s58, s50
	s_add_u32 s98, s42, 0x80
	s_addc_u32 s99, s43, 0
	s_add_u32 s100, s44, 0x80
	s_addc_u32 s101, s45, 0
	s_mov_b32 m0, s38
	ds_read_b128 v[180:183], v179 offset:49152
	ds_read_b128 v[184:187], v179 offset:50176
	ds_read_b128 v[188:191], v179 offset:51200
	ds_read_b128 v[192:195], v179 offset:52224
	ds_read_b128 v[196:199], v179 offset:53248
	ds_read_b128 v[200:203], v179 offset:54272
	ds_read_b128 v[204:207], v179 offset:55296
	ds_read_b128 v[208:211], v179 offset:56320
	global_load_lds_dwordx4 v130, s[98:99]
	s_add_i32 m0, s38, 0x2000
	s_add_u32 s38, s42, 0x300080
	s_addc_u32 s39, s43, 0
	s_add_i32 s42, s59, s50
	global_load_lds_dwordx4 v132, s[98:99]
	s_mov_b32 m0, s42
	s_nop 0
	global_load_lds_dwordx4 v130, s[38:39]
	s_add_i32 m0, s42, 0x2000
	s_nop 0
	global_load_lds_dwordx4 v132, s[38:39]
	s_mov_b32 m0, s57
	s_nop 0
	global_load_lds_dwordx4 v130, s[100:101]
	s_mov_b32 m0, s60
	s_nop 0
	global_load_lds_dwordx4 v132, s[100:101]
	s_waitcnt vmcnt(8)
	s_waitcnt lgkmcnt(0)
	s_barrier
	s_waitcnt lgkmcnt(0)
	v_mfma_f32_16x16x32_bf16 v[62:65], v[144:147], v[180:183], v[62:65]
	v_mfma_f32_16x16x32_bf16 v[62:65], v[148:151], v[184:187], v[62:65]
	v_mfma_f32_16x16x32_bf16 v[58:61], v[152:155], v[180:183], v[58:61]
	v_mfma_f32_16x16x32_bf16 v[58:61], v[156:159], v[184:187], v[58:61]
	v_mfma_f32_16x16x32_bf16 v[42:45], v[152:155], v[188:191], v[42:45]
	v_mfma_f32_16x16x32_bf16 v[42:45], v[156:159], v[192:195], v[42:45]
	v_mfma_f32_16x16x32_bf16 v[46:49], v[144:147], v[188:191], v[46:49]
	v_mfma_f32_16x16x32_bf16 v[46:49], v[148:151], v[192:195], v[46:49]
	v_mfma_f32_16x16x32_bf16 v[30:33], v[144:147], v[196:199], v[30:33]
	v_mfma_f32_16x16x32_bf16 v[30:33], v[148:151], v[200:203], v[30:33]
	v_mfma_f32_16x16x32_bf16 v[26:29], v[152:155], v[196:199], v[26:29]
	v_mfma_f32_16x16x32_bf16 v[26:29], v[156:159], v[200:203], v[26:29]
	v_mfma_f32_16x16x32_bf16 v[10:13], v[152:155], v[204:207], v[10:13]
	v_mfma_f32_16x16x32_bf16 v[10:13], v[156:159], v[208:211], v[10:13]
	v_mfma_f32_16x16x32_bf16 v[14:17], v[144:147], v[204:207], v[14:17]
	v_mfma_f32_16x16x32_bf16 v[14:17], v[148:151], v[208:211], v[14:17]
	v_mfma_f32_16x16x32_bf16 v[54:57], v[160:163], v[180:183], v[54:57]
	v_mfma_f32_16x16x32_bf16 v[54:57], v[164:167], v[184:187], v[54:57]
	v_mfma_f32_16x16x32_bf16 v[50:53], v[168:171], v[180:183], v[50:53]
	v_mfma_f32_16x16x32_bf16 v[50:53], v[172:175], v[184:187], v[50:53]
	v_mfma_f32_16x16x32_bf16 v[34:37], v[168:171], v[188:191], v[34:37]
	v_mfma_f32_16x16x32_bf16 v[34:37], v[172:175], v[192:195], v[34:37]
	v_mfma_f32_16x16x32_bf16 v[38:41], v[160:163], v[188:191], v[38:41]
	v_mfma_f32_16x16x32_bf16 v[38:41], v[164:167], v[192:195], v[38:41]
	v_mfma_f32_16x16x32_bf16 v[22:25], v[160:163], v[196:199], v[22:25]
	v_mfma_f32_16x16x32_bf16 v[22:25], v[164:167], v[200:203], v[22:25]
	v_mfma_f32_16x16x32_bf16 v[18:21], v[168:171], v[196:199], v[18:21]
	v_mfma_f32_16x16x32_bf16 v[18:21], v[172:175], v[200:203], v[18:21]
	v_mfma_f32_16x16x32_bf16 v[2:5], v[168:171], v[204:207], v[2:5]
	v_mfma_f32_16x16x32_bf16 v[2:5], v[172:175], v[208:211], v[2:5]
	v_mfma_f32_16x16x32_bf16 v[6:9], v[160:163], v[204:207], v[6:9]
	v_mfma_f32_16x16x32_bf16 v[6:9], v[164:167], v[208:211], v[6:9]
	s_barrier
	s_add_i32 s42, s71, 2
	s_add_u32 s31, s31, 0x100
	s_addc_u32 s70, s70, 0
	s_cmp_ge_i32 s71, s69
	s_mov_b64 s[38:39], s[40:41]
	s_mov_b32 s71, s42
	s_cbranch_scc0 .LBB0_3522
	s_and_b64 vcc, exec, s[20:21]
	s_cbranch_vccz .LBB0_3543
	s_barrier
	v_lshl_or_b32 v144, s5, 8, v176
	s_cmpk_eq_i32 s69, 0xc0
	s_mov_b64 s[38:39], -1
	s_cbranch_scc0 .LBB0_3544
